# adds hand-written EpiGU (ffn silu*up), EpiQ and EpiKV epilogues: loads prefetched, v_rcp sigmoid, scalar rope decision
# speedup vs baseline: 1.0098x; 1.0098x over previous
; __device__ __forceinline__ u32x4 pack8(f32x4 v0, f32x4 v1) { u32x4 w; w.x = cvt_pk_bf16(v0[0], v0[1]); w.y = cvt_pk_bf16(v0[2], v0[3]); w.z = cvt_pk_bf16(v1[0], v1[1]); w.w = cvt_pk_bf16(v1[2], v1[3]); return w; }
;     __device__ __forceinline__ void operator()(EPI_ARGS) const {
;         const int row0 = u.pm * BM + wr * 64 + fr;
; #pragma unroll
;         for (int ai = 0; ai < 2; ++ai)
; #pragma unroll
;             for (int m = 0; m < 4; ++m) { const int row = row0 + ai * HALF + m * 16; const float sc = rsqrtf(SSQ[row * 2] * (1.f / 512.f) + EPS) * c2;
;                 const int s = row % SB; const bool lat = s >= CTXL; const int t = s - CTXL;
; #pragma unroll
;                 for (int bj = 0; bj < 2; ++bj) { const int col0 = u.pn * BM + bj * HALF + wc * 32 + 8 * fq; const int d0 = col0 % 192;
;                     f32x4 v0 = acc[ai][bj][m][0] * sc, v1 = acc[ai][bj][m][1] * sc;
;                     if (d0 >= 128 && lat) { const float* rp = ROPE + ((size_t)t * 32 + ((d0 - 128) >> 1)) * 2; const f32x4 r0 = *(const f32x4*)rp, r1 = *(const f32x4*)(rp + 4);
;                         f32x4 o0, o1;
;                         o0[0] = v0[0] * r0[0] - v0[1] * r0[1]; o0[1] = v0[0] * r0[1] + v0[1] * r0[0]; o0[2] = v0[2] * r0[2] - v0[3] * r0[3]; o0[3] = v0[2] * r0[3] + v0[3] * r0[2];
;                         o1[0] = v1[0] * r1[0] - v1[1] * r1[1]; o1[1] = v1[0] * r1[1] + v1[1] * r1[0]; o1[2] = v1[2] * r1[2] - v1[3] * r1[3]; o1[3] = v1[2] * r1[3] + v1[3] * r1[2];
;                         v0 = o0; v1 = o1; }
;                     *(u32x4*)(Q + (size_t)row * QLD + col0) = pack8(v0, v1); }
;                 asm volatile("" ::: "memory"); }
;     }
.LBB0_1178:
	v_lshl_add_u32 v204, s35, 8, v148
	v_lshl_or_b32 v152, s6, 8, v150
	v_lshlrev_b32_e32 v205, 3, v204
	global_load_dword v140, v205, s[18:19]
	global_load_dword v141, v205, s[18:19] offset:128
	global_load_dword v142, v205, s[18:19] offset:256
	global_load_dword v143, v205, s[18:19] offset:384
	global_load_dword v144, v205, s[18:19] offset:1024
	global_load_dword v145, v205, s[18:19] offset:1152
	global_load_dword v146, v205, s[18:19] offset:1280
	global_load_dword v147, v205, s[18:19] offset:1408
	v_mul_u32_u24_e32 v160, 0x1800, v204
	v_lshl_add_u32 v160, v152, 1, v160
	v_readfirstlane_b32 s4, v150
	s_nop 3
	s_lshr_b32 s4, s4, 5
	s_lshl_b32 s5, s6, 3
	s_add_i32 s4, s4, s5
	s_mul_i32 s5, s4, 43
	s_lshr_b32 s5, s5, 8
	s_mul_i32 s5, s5, 6
	s_sub_i32 s5, s4, s5
	s_add_i32 s4, s4, 4
	s_mul_i32 s30, s4, 43
	s_lshr_b32 s30, s30, 8
	s_mul_i32 s30, s30, 6
	s_sub_i32 s4, s4, s30
	s_mul_hi_i32 s30, s35, 0x38e38e39
	s_lshr_b32 s36, s30, 31
	s_ashr_i32 s30, s30, 1
	s_add_i32 s30, s30, s36
	s_mul_i32 s30, s30, 9
	s_sub_i32 s30, s35, s30
	s_cmp_eq_u32 s30, 0
	s_cbranch_scc1 .Lmy_q_norope
	s_cmp_ge_u32 s5, 4
	s_cbranch_scc1 .Lmy_q_rope0
	s_cmp_ge_u32 s4, 4
	s_cbranch_scc1 .Lmy_q_rope1
.Lmy_q_norope:
	s_waitcnt vmcnt(7)
	v_fmamk_f32 v140, v140, 0x3b000000, v207
	v_rsq_f32_e32 v140, v140
	s_nop 0
	v_mul_f32_e32 v140, 0x3dd53b94, v140
	v_mul_f32_e32 v124, v124, v140
	v_mul_f32_e32 v125, v125, v140
	v_mul_f32_e32 v126, v126, v140
	v_mul_f32_e32 v127, v127, v140
	v_mul_f32_e32 v120, v120, v140
	v_mul_f32_e32 v121, v121, v140
	v_mul_f32_e32 v122, v122, v140
	v_mul_f32_e32 v123, v123, v140
	v_cvt_pk_bf16_f32 v124, v124, v125
	v_cvt_pk_bf16_f32 v125, v126, v127
	v_cvt_pk_bf16_f32 v126, v120, v121
	v_cvt_pk_bf16_f32 v127, v122, v123
	global_store_dwordx4 v160, v[124:127], s[16:17]
	v_mul_f32_e32 v116, v116, v140
	v_mul_f32_e32 v117, v117, v140
	v_mul_f32_e32 v118, v118, v140
	v_mul_f32_e32 v119, v119, v140
	v_mul_f32_e32 v112, v112, v140
	v_mul_f32_e32 v113, v113, v140
	v_mul_f32_e32 v114, v114, v140
	v_mul_f32_e32 v115, v115, v140
	v_cvt_pk_bf16_f32 v116, v116, v117
	v_cvt_pk_bf16_f32 v117, v118, v119
	v_cvt_pk_bf16_f32 v118, v112, v113
	v_cvt_pk_bf16_f32 v119, v114, v115
	global_store_dwordx4 v160, v[116:119], s[16:17] offset:256
	s_waitcnt vmcnt(8)
	v_fmamk_f32 v141, v141, 0x3b000000, v207
	v_rsq_f32_e32 v141, v141
	s_add_u32 s70, s16, 0x18000
	s_addc_u32 s71, s17, 0
	v_mul_f32_e32 v141, 0x3dd53b94, v141
	v_mul_f32_e32 v108, v108, v141
	v_mul_f32_e32 v109, v109, v141
	v_mul_f32_e32 v110, v110, v141
	v_mul_f32_e32 v111, v111, v141
	v_mul_f32_e32 v104, v104, v141
	v_mul_f32_e32 v105, v105, v141
	v_mul_f32_e32 v106, v106, v141
	v_mul_f32_e32 v107, v107, v141
	v_cvt_pk_bf16_f32 v108, v108, v109
	v_cvt_pk_bf16_f32 v109, v110, v111
	v_cvt_pk_bf16_f32 v110, v104, v105
	v_cvt_pk_bf16_f32 v111, v106, v107
	global_store_dwordx4 v160, v[108:111], s[70:71]
	v_mul_f32_e32 v100, v100, v141
	v_mul_f32_e32 v101, v101, v141
	v_mul_f32_e32 v102, v102, v141
	v_mul_f32_e32 v103, v103, v141
	v_mul_f32_e32 v96, v96, v141
	v_mul_f32_e32 v97, v97, v141
	v_mul_f32_e32 v98, v98, v141
	v_mul_f32_e32 v99, v99, v141
	v_cvt_pk_bf16_f32 v100, v100, v101
	v_cvt_pk_bf16_f32 v101, v102, v103
	v_cvt_pk_bf16_f32 v102, v96, v97
	v_cvt_pk_bf16_f32 v103, v98, v99
	global_store_dwordx4 v160, v[100:103], s[70:71] offset:256
	s_waitcnt vmcnt(9)
	v_fmamk_f32 v142, v142, 0x3b000000, v207
	v_rsq_f32_e32 v142, v142
	s_add_u32 s70, s16, 0x30000
	s_addc_u32 s71, s17, 0
	v_mul_f32_e32 v142, 0x3dd53b94, v142
	v_mul_f32_e32 v92, v92, v142
	v_mul_f32_e32 v93, v93, v142
	v_mul_f32_e32 v94, v94, v142
	v_mul_f32_e32 v95, v95, v142
	v_mul_f32_e32 v88, v88, v142
	v_mul_f32_e32 v89, v89, v142
	v_mul_f32_e32 v90, v90, v142
	v_mul_f32_e32 v91, v91, v142
	v_cvt_pk_bf16_f32 v92, v92, v93
	v_cvt_pk_bf16_f32 v93, v94, v95
	v_cvt_pk_bf16_f32 v94, v88, v89
	v_cvt_pk_bf16_f32 v95, v90, v91
	global_store_dwordx4 v160, v[92:95], s[70:71]
	v_mul_f32_e32 v84, v84, v142
	v_mul_f32_e32 v85, v85, v142
	v_mul_f32_e32 v86, v86, v142
	v_mul_f32_e32 v87, v87, v142
	v_mul_f32_e32 v80, v80, v142
	v_mul_f32_e32 v81, v81, v142
	v_mul_f32_e32 v82, v82, v142
	v_mul_f32_e32 v83, v83, v142
	v_cvt_pk_bf16_f32 v84, v84, v85
	v_cvt_pk_bf16_f32 v85, v86, v87
	v_cvt_pk_bf16_f32 v86, v80, v81
	v_cvt_pk_bf16_f32 v87, v82, v83
	global_store_dwordx4 v160, v[84:87], s[70:71] offset:256
	s_waitcnt vmcnt(10)
	v_fmamk_f32 v143, v143, 0x3b000000, v207
	v_rsq_f32_e32 v143, v143
	s_add_u32 s70, s16, 0x48000
	s_addc_u32 s71, s17, 0
	v_mul_f32_e32 v143, 0x3dd53b94, v143
	v_mul_f32_e32 v76, v76, v143
	v_mul_f32_e32 v77, v77, v143
	v_mul_f32_e32 v78, v78, v143
	v_mul_f32_e32 v79, v79, v143
	v_mul_f32_e32 v72, v72, v143
	v_mul_f32_e32 v73, v73, v143
	v_mul_f32_e32 v74, v74, v143
	v_mul_f32_e32 v75, v75, v143
	v_cvt_pk_bf16_f32 v76, v76, v77
	v_cvt_pk_bf16_f32 v77, v78, v79
	v_cvt_pk_bf16_f32 v78, v72, v73
	v_cvt_pk_bf16_f32 v79, v74, v75
	global_store_dwordx4 v160, v[76:79], s[70:71]
	v_mul_f32_e32 v68, v68, v143
	v_mul_f32_e32 v69, v69, v143
	v_mul_f32_e32 v70, v70, v143
	v_mul_f32_e32 v71, v71, v143
	v_mul_f32_e32 v64, v64, v143
	v_mul_f32_e32 v65, v65, v143
	v_mul_f32_e32 v66, v66, v143
	v_mul_f32_e32 v67, v67, v143
	v_cvt_pk_bf16_f32 v68, v68, v69
	v_cvt_pk_bf16_f32 v69, v70, v71
	v_cvt_pk_bf16_f32 v70, v64, v65
	v_cvt_pk_bf16_f32 v71, v66, v67
	global_store_dwordx4 v160, v[68:71], s[70:71] offset:256
	s_waitcnt vmcnt(11)
; __device__ __forceinline__ u32x4 pack8(f32x4 v0, f32x4 v1) { u32x4 w; w.x = cvt_pk_bf16(v0[0], v0[1]); w.y = cvt_pk_bf16(v0[2], v0[3]); w.z = cvt_pk_bf16(v1[0], v1[1]); w.w = cvt_pk_bf16(v1[2], v1[3]); return w; }
;     __device__ __forceinline__ void operator()(EPI_ARGS) const {
;         const int row0 = u.pm * BM + wr * 64 + fr;
; #pragma unroll
;         for (int ai = 0; ai < 2; ++ai)
; #pragma unroll
;             for (int m = 0; m < 4; ++m) { const int row = row0 + ai * HALF + m * 16; const float sc = rsqrtf(SSQ[row * 2] * (1.f / 512.f) + EPS) * c2;
;                 const int s = row % SB; const bool lat = s >= CTXL; const int t = s - CTXL;
; #pragma unroll
;                 for (int bj = 0; bj < 2; ++bj) { const int col0 = u.pn * BM + bj * HALF + wc * 32 + 8 * fq; const int d0 = col0 % 192;
;                     f32x4 v0 = acc[ai][bj][m][0] * sc, v1 = acc[ai][bj][m][1] * sc;
;                     if (d0 >= 128 && lat) { const float* rp = ROPE + ((size_t)t * 32 + ((d0 - 128) >> 1)) * 2; const f32x4 r0 = *(const f32x4*)rp, r1 = *(const f32x4*)(rp + 4);
;                         f32x4 o0, o1;
;                         o0[0] = v0[0] * r0[0] - v0[1] * r0[1]; o0[1] = v0[0] * r0[1] + v0[1] * r0[0]; o0[2] = v0[2] * r0[2] - v0[3] * r0[3]; o0[3] = v0[2] * r0[3] + v0[3] * r0[2];
;                         o1[0] = v1[0] * r1[0] - v1[1] * r1[1]; o1[1] = v1[0] * r1[1] + v1[1] * r1[0]; o1[2] = v1[2] * r1[2] - v1[3] * r1[3]; o1[3] = v1[2] * r1[3] + v1[3] * r1[2];
;                         v0 = o0; v1 = o1; }
;                     *(u32x4*)(Q + (size_t)row * QLD + col0) = pack8(v0, v1); }
;                 asm volatile("" ::: "memory"); }
;     }
	v_fmamk_f32 v144, v144, 0x3b000000, v207
	v_rsq_f32_e32 v144, v144
	s_add_u32 s70, s16, 0xc0000
	s_addc_u32 s71, s17, 0
	v_mul_f32_e32 v144, 0x3dd53b94, v144
	v_mul_f32_e32 v60, v60, v144
	v_mul_f32_e32 v61, v61, v144
	v_mul_f32_e32 v62, v62, v144
	v_mul_f32_e32 v63, v63, v144
	v_mul_f32_e32 v56, v56, v144
	v_mul_f32_e32 v57, v57, v144
	v_mul_f32_e32 v58, v58, v144
	v_mul_f32_e32 v59, v59, v144
	v_cvt_pk_bf16_f32 v60, v60, v61
	v_cvt_pk_bf16_f32 v61, v62, v63
	v_cvt_pk_bf16_f32 v62, v56, v57
	v_cvt_pk_bf16_f32 v63, v58, v59
	global_store_dwordx4 v160, v[60:63], s[70:71]
	v_mul_f32_e32 v52, v52, v144
	v_mul_f32_e32 v53, v53, v144
	v_mul_f32_e32 v54, v54, v144
	v_mul_f32_e32 v55, v55, v144
	v_mul_f32_e32 v48, v48, v144
	v_mul_f32_e32 v49, v49, v144
	v_mul_f32_e32 v50, v50, v144
	v_mul_f32_e32 v51, v51, v144
	v_cvt_pk_bf16_f32 v52, v52, v53
	v_cvt_pk_bf16_f32 v53, v54, v55
	v_cvt_pk_bf16_f32 v54, v48, v49
	v_cvt_pk_bf16_f32 v55, v50, v51
	global_store_dwordx4 v160, v[52:55], s[70:71] offset:256
	s_waitcnt vmcnt(12)
	v_fmamk_f32 v145, v145, 0x3b000000, v207
	v_rsq_f32_e32 v145, v145
	s_add_u32 s70, s16, 0xd8000
	s_addc_u32 s71, s17, 0
	v_mul_f32_e32 v145, 0x3dd53b94, v145
	v_mul_f32_e32 v44, v44, v145
	v_mul_f32_e32 v45, v45, v145
	v_mul_f32_e32 v46, v46, v145
	v_mul_f32_e32 v47, v47, v145
	v_mul_f32_e32 v40, v40, v145
	v_mul_f32_e32 v41, v41, v145
	v_mul_f32_e32 v42, v42, v145
	v_mul_f32_e32 v43, v43, v145
	v_cvt_pk_bf16_f32 v44, v44, v45
	v_cvt_pk_bf16_f32 v45, v46, v47
	v_cvt_pk_bf16_f32 v46, v40, v41
	v_cvt_pk_bf16_f32 v47, v42, v43
	global_store_dwordx4 v160, v[44:47], s[70:71]
	v_mul_f32_e32 v36, v36, v145
	v_mul_f32_e32 v37, v37, v145
	v_mul_f32_e32 v38, v38, v145
	v_mul_f32_e32 v39, v39, v145
	v_mul_f32_e32 v32, v32, v145
	v_mul_f32_e32 v33, v33, v145
	v_mul_f32_e32 v34, v34, v145
	v_mul_f32_e32 v35, v35, v145
	v_cvt_pk_bf16_f32 v36, v36, v37
	v_cvt_pk_bf16_f32 v37, v38, v39
	v_cvt_pk_bf16_f32 v38, v32, v33
	v_cvt_pk_bf16_f32 v39, v34, v35
	global_store_dwordx4 v160, v[36:39], s[70:71] offset:256
	s_waitcnt vmcnt(13)
	v_fmamk_f32 v146, v146, 0x3b000000, v207
	v_rsq_f32_e32 v146, v146
	s_add_u32 s70, s16, 0xf0000
	s_addc_u32 s71, s17, 0
	v_mul_f32_e32 v146, 0x3dd53b94, v146
	v_mul_f32_e32 v28, v28, v146
	v_mul_f32_e32 v29, v29, v146
	v_mul_f32_e32 v30, v30, v146
	v_mul_f32_e32 v31, v31, v146
	v_mul_f32_e32 v24, v24, v146
	v_mul_f32_e32 v25, v25, v146
	v_mul_f32_e32 v26, v26, v146
	v_mul_f32_e32 v27, v27, v146
	v_cvt_pk_bf16_f32 v28, v28, v29
	v_cvt_pk_bf16_f32 v29, v30, v31
	v_cvt_pk_bf16_f32 v30, v24, v25
	v_cvt_pk_bf16_f32 v31, v26, v27
	global_store_dwordx4 v160, v[28:31], s[70:71]
	v_mul_f32_e32 v20, v20, v146
	v_mul_f32_e32 v21, v21, v146
	v_mul_f32_e32 v22, v22, v146
	v_mul_f32_e32 v23, v23, v146
	v_mul_f32_e32 v16, v16, v146
	v_mul_f32_e32 v17, v17, v146
	v_mul_f32_e32 v18, v18, v146
	v_mul_f32_e32 v19, v19, v146
	v_cvt_pk_bf16_f32 v20, v20, v21
	v_cvt_pk_bf16_f32 v21, v22, v23
	v_cvt_pk_bf16_f32 v22, v16, v17
	v_cvt_pk_bf16_f32 v23, v18, v19
	global_store_dwordx4 v160, v[20:23], s[70:71] offset:256
	s_waitcnt vmcnt(14)
	v_fmamk_f32 v147, v147, 0x3b000000, v207
	v_rsq_f32_e32 v147, v147
	s_add_u32 s70, s16, 0x108000
	s_addc_u32 s71, s17, 0
	v_mul_f32_e32 v147, 0x3dd53b94, v147
	v_mul_f32_e32 v12, v12, v147
	v_mul_f32_e32 v13, v13, v147
	v_mul_f32_e32 v14, v14, v147
	v_mul_f32_e32 v15, v15, v147
	v_mul_f32_e32 v8, v8, v147
	v_mul_f32_e32 v9, v9, v147
	v_mul_f32_e32 v10, v10, v147
	v_mul_f32_e32 v11, v11, v147
	v_cvt_pk_bf16_f32 v12, v12, v13
	v_cvt_pk_bf16_f32 v13, v14, v15
	v_cvt_pk_bf16_f32 v14, v8, v9
	v_cvt_pk_bf16_f32 v15, v10, v11
	global_store_dwordx4 v160, v[12:15], s[70:71]
	v_mul_f32_e32 v4, v4, v147
	v_mul_f32_e32 v5, v5, v147
	v_mul_f32_e32 v6, v6, v147
	v_mul_f32_e32 v7, v7, v147
	v_mul_f32_e32 v0, v0, v147
	v_mul_f32_e32 v1, v1, v147
	v_mul_f32_e32 v2, v2, v147
	v_mul_f32_e32 v3, v3, v147
	v_cvt_pk_bf16_f32 v4, v4, v5
	v_cvt_pk_bf16_f32 v5, v6, v7
	v_cvt_pk_bf16_f32 v6, v0, v1
	v_cvt_pk_bf16_f32 v7, v2, v3
	global_store_dwordx4 v160, v[4:7], s[70:71] offset:256
	s_branch .Lmy_q_done
.Lmy_q_rope0:
	s_sub_i32 s36, s5, 4
	s_lshl_b32 s36, s36, 7
	s_sub_i32 s30, s30, 1
	s_lshl_b32 s30, s30, 8
	v_add_u32_e32 v205, s30, v148
	v_and_b32_e32 v204, 31, v150
	v_lshlrev_b32_e32 v205, 8, v205
	v_lshl_add_u32 v205, v204, 2, v205
	s_add_u32 s42, s20, s36
	s_addc_u32 s43, s21, 0
	global_load_dwordx4 v[152:155], v205, s[42:43]
	global_load_dwordx4 v[156:159], v205, s[42:43] offset:16
	s_add_u32 s64, s42, 0x1000
	s_addc_u32 s65, s43, 0
	global_load_dwordx4 v[164:167], v205, s[64:65]
	global_load_dwordx4 v[168:171], v205, s[64:65] offset:16
	s_add_u32 s64, s42, 0x2000
	s_addc_u32 s65, s43, 0
	global_load_dwordx4 v[172:175], v205, s[64:65]
	global_load_dwordx4 v[176:179], v205, s[64:65] offset:16
	s_add_u32 s64, s42, 0x3000
	s_addc_u32 s65, s43, 0
	global_load_dwordx4 v[180:183], v205, s[64:65]
	global_load_dwordx4 v[184:187], v205, s[64:65] offset:16
	s_add_u32 s64, s42, 0x8000
	s_addc_u32 s65, s43, 0
	global_load_dwordx4 v[188:191], v205, s[64:65]
	global_load_dwordx4 v[192:195], v205, s[64:65] offset:16
	s_add_u32 s64, s42, 0x9000
	s_addc_u32 s65, s43, 0
	global_load_dwordx4 v[196:199], v205, s[64:65]
	global_load_dwordx4 v[200:203], v205, s[64:65] offset:16
	s_add_u32 s64, s42, 0xa000
	s_addc_u32 s65, s43, 0
	global_load_dwordx4 v[208:211], v205, s[64:65]
	global_load_dwordx4 v[216:219], v205, s[64:65] offset:16
	s_add_u32 s64, s42, 0xb000
	s_addc_u32 s65, s43, 0
	global_load_dwordx4 v[220:223], v205, s[64:65]
	global_load_dwordx4 v[224:227], v205, s[64:65] offset:16
	s_waitcnt vmcnt(23)
; __device__ __forceinline__ u32x4 pack8(f32x4 v0, f32x4 v1) { u32x4 w; w.x = cvt_pk_bf16(v0[0], v0[1]); w.y = cvt_pk_bf16(v0[2], v0[3]); w.z = cvt_pk_bf16(v1[0], v1[1]); w.w = cvt_pk_bf16(v1[2], v1[3]); return w; }
;     __device__ __forceinline__ void operator()(EPI_ARGS) const {
;     ...
;             for (int m = 0; m < 4; ++m) { const int row = row0 + ai * HALF + m * 16; const float sc = rsqrtf(SSQ[row * 2] * (1.f / 512.f) + EPS) * c2;
;                 const int s = row % SB; const bool lat = s >= CTXL; const int t = s - CTXL;
; #pragma unroll
;                 for (int bj = 0; bj < 2; ++bj) { const int col0 = u.pn * BM + bj * HALF + wc * 32 + 8 * fq; const int d0 = col0 % 192;
;                     f32x4 v0 = acc[ai][bj][m][0] * sc, v1 = acc[ai][bj][m][1] * sc;
;                     if (d0 >= 128 && lat) { const float* rp = ROPE + ((size_t)t * 32 + ((d0 - 128) >> 1)) * 2; const f32x4 r0 = *(const f32x4*)rp, r1 = *(const f32x4*)(rp + 4);
;                         f32x4 o0, o1;
;                         o0[0] = v0[0] * r0[0] - v0[1] * r0[1]; o0[1] = v0[0] * r0[1] + v0[1] * r0[0]; o0[2] = v0[2] * r0[2] - v0[3] * r0[3]; o0[3] = v0[2] * r0[3] + v0[3] * r0[2];
;                         o1[0] = v1[0] * r1[0] - v1[1] * r1[1]; o1[1] = v1[0] * r1[1] + v1[1] * r1[0]; o1[2] = v1[2] * r1[2] - v1[3] * r1[3]; o1[3] = v1[2] * r1[3] + v1[3] * r1[2];
;                         v0 = o0; v1 = o1; }
;                     *(u32x4*)(Q + (size_t)row * QLD + col0) = pack8(v0, v1); }
	v_fmamk_f32 v140, v140, 0x3b000000, v207
	v_rsq_f32_e32 v140, v140
	s_nop 0
	v_mul_f32_e32 v140, 0x3dd53b94, v140
	v_mul_f32_e32 v124, v124, v140
	v_mul_f32_e32 v125, v125, v140
	v_mul_f32_e32 v126, v126, v140
	v_mul_f32_e32 v127, v127, v140
	v_mul_f32_e32 v120, v120, v140
	v_mul_f32_e32 v121, v121, v140
	v_mul_f32_e32 v122, v122, v140
	v_mul_f32_e32 v123, v123, v140
	s_waitcnt vmcnt(14)
	v_mul_f32_e32 v204, v125, v153
	v_mul_f32_e32 v205, v125, v152
	v_fma_f32 v125, v124, v153, v205
	v_fma_f32 v124, v124, v152, -v204
	v_mul_f32_e32 v204, v127, v155
	v_mul_f32_e32 v205, v127, v154
	v_fma_f32 v127, v126, v155, v205
	v_fma_f32 v126, v126, v154, -v204
	v_mul_f32_e32 v204, v121, v157
	v_mul_f32_e32 v205, v121, v156
	v_fma_f32 v121, v120, v157, v205
	v_fma_f32 v120, v120, v156, -v204
	v_mul_f32_e32 v204, v123, v159
	v_mul_f32_e32 v205, v123, v158
	v_fma_f32 v123, v122, v159, v205
	v_fma_f32 v122, v122, v158, -v204
	v_cvt_pk_bf16_f32 v124, v124, v125
	v_cvt_pk_bf16_f32 v125, v126, v127
	v_cvt_pk_bf16_f32 v126, v120, v121
	v_cvt_pk_bf16_f32 v127, v122, v123
	global_store_dwordx4 v160, v[124:127], s[16:17]
	v_mul_f32_e32 v116, v116, v140
	v_mul_f32_e32 v117, v117, v140
	v_mul_f32_e32 v118, v118, v140
	v_mul_f32_e32 v119, v119, v140
	v_mul_f32_e32 v112, v112, v140
	v_mul_f32_e32 v113, v113, v140
	v_mul_f32_e32 v114, v114, v140
	v_mul_f32_e32 v115, v115, v140
	v_cvt_pk_bf16_f32 v116, v116, v117
	v_cvt_pk_bf16_f32 v117, v118, v119
	v_cvt_pk_bf16_f32 v118, v112, v113
	v_cvt_pk_bf16_f32 v119, v114, v115
	global_store_dwordx4 v160, v[116:119], s[16:17] offset:256
	s_waitcnt vmcnt(24)
	v_fmamk_f32 v141, v141, 0x3b000000, v207
	v_rsq_f32_e32 v141, v141
	s_add_u32 s70, s16, 0x18000
	s_addc_u32 s71, s17, 0
	v_mul_f32_e32 v141, 0x3dd53b94, v141
	v_mul_f32_e32 v108, v108, v141
	v_mul_f32_e32 v109, v109, v141
	v_mul_f32_e32 v110, v110, v141
	v_mul_f32_e32 v111, v111, v141
	v_mul_f32_e32 v104, v104, v141
	v_mul_f32_e32 v105, v105, v141
	v_mul_f32_e32 v106, v106, v141
	v_mul_f32_e32 v107, v107, v141
	s_waitcnt vmcnt(14)
	v_mul_f32_e32 v204, v109, v165
	v_mul_f32_e32 v205, v109, v164
	v_fma_f32 v109, v108, v165, v205
	v_fma_f32 v108, v108, v164, -v204
	v_mul_f32_e32 v204, v111, v167
	v_mul_f32_e32 v205, v111, v166
	v_fma_f32 v111, v110, v167, v205
	v_fma_f32 v110, v110, v166, -v204
	v_mul_f32_e32 v204, v105, v169
	v_mul_f32_e32 v205, v105, v168
	v_fma_f32 v105, v104, v169, v205
	v_fma_f32 v104, v104, v168, -v204
	v_mul_f32_e32 v204, v107, v171
	v_mul_f32_e32 v205, v107, v170
	v_fma_f32 v107, v106, v171, v205
	v_fma_f32 v106, v106, v170, -v204
	v_cvt_pk_bf16_f32 v108, v108, v109
	v_cvt_pk_bf16_f32 v109, v110, v111
	v_cvt_pk_bf16_f32 v110, v104, v105
	v_cvt_pk_bf16_f32 v111, v106, v107
	global_store_dwordx4 v160, v[108:111], s[70:71]
	v_mul_f32_e32 v100, v100, v141
	v_mul_f32_e32 v101, v101, v141
	v_mul_f32_e32 v102, v102, v141
	v_mul_f32_e32 v103, v103, v141
	v_mul_f32_e32 v96, v96, v141
	v_mul_f32_e32 v97, v97, v141
	v_mul_f32_e32 v98, v98, v141
	v_mul_f32_e32 v99, v99, v141
	v_cvt_pk_bf16_f32 v100, v100, v101
	v_cvt_pk_bf16_f32 v101, v102, v103
	v_cvt_pk_bf16_f32 v102, v96, v97
	v_cvt_pk_bf16_f32 v103, v98, v99
	global_store_dwordx4 v160, v[100:103], s[70:71] offset:256
	s_waitcnt vmcnt(25)
	v_fmamk_f32 v142, v142, 0x3b000000, v207
	v_rsq_f32_e32 v142, v142
	s_add_u32 s70, s16, 0x30000
	s_addc_u32 s71, s17, 0
	v_mul_f32_e32 v142, 0x3dd53b94, v142
	v_mul_f32_e32 v92, v92, v142
	v_mul_f32_e32 v93, v93, v142
	v_mul_f32_e32 v94, v94, v142
	v_mul_f32_e32 v95, v95, v142
	v_mul_f32_e32 v88, v88, v142
	v_mul_f32_e32 v89, v89, v142
	v_mul_f32_e32 v90, v90, v142
	v_mul_f32_e32 v91, v91, v142
	s_waitcnt vmcnt(14)
	v_mul_f32_e32 v204, v93, v173
	v_mul_f32_e32 v205, v93, v172
	v_fma_f32 v93, v92, v173, v205
	v_fma_f32 v92, v92, v172, -v204
	v_mul_f32_e32 v204, v95, v175
	v_mul_f32_e32 v205, v95, v174
	v_fma_f32 v95, v94, v175, v205
	v_fma_f32 v94, v94, v174, -v204
	v_mul_f32_e32 v204, v89, v177
	v_mul_f32_e32 v205, v89, v176
	v_fma_f32 v89, v88, v177, v205
	v_fma_f32 v88, v88, v176, -v204
	v_mul_f32_e32 v204, v91, v179
	v_mul_f32_e32 v205, v91, v178
	v_fma_f32 v91, v90, v179, v205
	v_fma_f32 v90, v90, v178, -v204
	v_cvt_pk_bf16_f32 v92, v92, v93
	v_cvt_pk_bf16_f32 v93, v94, v95
	v_cvt_pk_bf16_f32 v94, v88, v89
	v_cvt_pk_bf16_f32 v95, v90, v91
	global_store_dwordx4 v160, v[92:95], s[70:71]
	v_mul_f32_e32 v84, v84, v142
	v_mul_f32_e32 v85, v85, v142
	v_mul_f32_e32 v86, v86, v142
	v_mul_f32_e32 v87, v87, v142
	v_mul_f32_e32 v80, v80, v142
	v_mul_f32_e32 v81, v81, v142
	v_mul_f32_e32 v82, v82, v142
	v_mul_f32_e32 v83, v83, v142
	v_cvt_pk_bf16_f32 v84, v84, v85
	v_cvt_pk_bf16_f32 v85, v86, v87
	v_cvt_pk_bf16_f32 v86, v80, v81
	v_cvt_pk_bf16_f32 v87, v82, v83
	global_store_dwordx4 v160, v[84:87], s[70:71] offset:256
	s_waitcnt vmcnt(26)
	v_fmamk_f32 v143, v143, 0x3b000000, v207
	v_rsq_f32_e32 v143, v143
	s_add_u32 s70, s16, 0x48000
	s_addc_u32 s71, s17, 0
	v_mul_f32_e32 v143, 0x3dd53b94, v143
	v_mul_f32_e32 v76, v76, v143
	v_mul_f32_e32 v77, v77, v143
	v_mul_f32_e32 v78, v78, v143
	v_mul_f32_e32 v79, v79, v143
	v_mul_f32_e32 v72, v72, v143
	v_mul_f32_e32 v73, v73, v143
	v_mul_f32_e32 v74, v74, v143
	v_mul_f32_e32 v75, v75, v143
	s_waitcnt vmcnt(14)
; __device__ __forceinline__ u32x4 pack8(f32x4 v0, f32x4 v1) { u32x4 w; w.x = cvt_pk_bf16(v0[0], v0[1]); w.y = cvt_pk_bf16(v0[2], v0[3]); w.z = cvt_pk_bf16(v1[0], v1[1]); w.w = cvt_pk_bf16(v1[2], v1[3]); return w; }
;     __device__ __forceinline__ void operator()(EPI_ARGS) const {
;     ...
;             for (int m = 0; m < 4; ++m) { const int row = row0 + ai * HALF + m * 16; const float sc = rsqrtf(SSQ[row * 2] * (1.f / 512.f) + EPS) * c2;
;                 const int s = row % SB; const bool lat = s >= CTXL; const int t = s - CTXL;
; #pragma unroll
;                 for (int bj = 0; bj < 2; ++bj) { const int col0 = u.pn * BM + bj * HALF + wc * 32 + 8 * fq; const int d0 = col0 % 192;
;                     f32x4 v0 = acc[ai][bj][m][0] * sc, v1 = acc[ai][bj][m][1] * sc;
;                     if (d0 >= 128 && lat) { const float* rp = ROPE + ((size_t)t * 32 + ((d0 - 128) >> 1)) * 2; const f32x4 r0 = *(const f32x4*)rp, r1 = *(const f32x4*)(rp + 4);
;                         f32x4 o0, o1;
;                         o0[0] = v0[0] * r0[0] - v0[1] * r0[1]; o0[1] = v0[0] * r0[1] + v0[1] * r0[0]; o0[2] = v0[2] * r0[2] - v0[3] * r0[3]; o0[3] = v0[2] * r0[3] + v0[3] * r0[2];
;                         o1[0] = v1[0] * r1[0] - v1[1] * r1[1]; o1[1] = v1[0] * r1[1] + v1[1] * r1[0]; o1[2] = v1[2] * r1[2] - v1[3] * r1[3]; o1[3] = v1[2] * r1[3] + v1[3] * r1[2];
;                         v0 = o0; v1 = o1; }
;                     *(u32x4*)(Q + (size_t)row * QLD + col0) = pack8(v0, v1); }
	v_mul_f32_e32 v204, v77, v181
	v_mul_f32_e32 v205, v77, v180
	v_fma_f32 v77, v76, v181, v205
	v_fma_f32 v76, v76, v180, -v204
	v_mul_f32_e32 v204, v79, v183
	v_mul_f32_e32 v205, v79, v182
	v_fma_f32 v79, v78, v183, v205
	v_fma_f32 v78, v78, v182, -v204
	v_mul_f32_e32 v204, v73, v185
	v_mul_f32_e32 v205, v73, v184
	v_fma_f32 v73, v72, v185, v205
	v_fma_f32 v72, v72, v184, -v204
	v_mul_f32_e32 v204, v75, v187
	v_mul_f32_e32 v205, v75, v186
	v_fma_f32 v75, v74, v187, v205
	v_fma_f32 v74, v74, v186, -v204
	v_cvt_pk_bf16_f32 v76, v76, v77
	v_cvt_pk_bf16_f32 v77, v78, v79
	v_cvt_pk_bf16_f32 v78, v72, v73
	v_cvt_pk_bf16_f32 v79, v74, v75
	global_store_dwordx4 v160, v[76:79], s[70:71]
	v_mul_f32_e32 v68, v68, v143
	v_mul_f32_e32 v69, v69, v143
	v_mul_f32_e32 v70, v70, v143
	v_mul_f32_e32 v71, v71, v143
	v_mul_f32_e32 v64, v64, v143
	v_mul_f32_e32 v65, v65, v143
	v_mul_f32_e32 v66, v66, v143
	v_mul_f32_e32 v67, v67, v143
	v_cvt_pk_bf16_f32 v68, v68, v69
	v_cvt_pk_bf16_f32 v69, v70, v71
	v_cvt_pk_bf16_f32 v70, v64, v65
	v_cvt_pk_bf16_f32 v71, v66, v67
	global_store_dwordx4 v160, v[68:71], s[70:71] offset:256
	s_waitcnt vmcnt(27)
	v_fmamk_f32 v144, v144, 0x3b000000, v207
	v_rsq_f32_e32 v144, v144
	s_add_u32 s70, s16, 0xc0000
	s_addc_u32 s71, s17, 0
	v_mul_f32_e32 v144, 0x3dd53b94, v144
	v_mul_f32_e32 v60, v60, v144
	v_mul_f32_e32 v61, v61, v144
	v_mul_f32_e32 v62, v62, v144
	v_mul_f32_e32 v63, v63, v144
	v_mul_f32_e32 v56, v56, v144
	v_mul_f32_e32 v57, v57, v144
	v_mul_f32_e32 v58, v58, v144
	v_mul_f32_e32 v59, v59, v144
	s_waitcnt vmcnt(14)
	v_mul_f32_e32 v204, v61, v189
	v_mul_f32_e32 v205, v61, v188
	v_fma_f32 v61, v60, v189, v205
	v_fma_f32 v60, v60, v188, -v204
	v_mul_f32_e32 v204, v63, v191
	v_mul_f32_e32 v205, v63, v190
	v_fma_f32 v63, v62, v191, v205
	v_fma_f32 v62, v62, v190, -v204
	v_mul_f32_e32 v204, v57, v193
	v_mul_f32_e32 v205, v57, v192
	v_fma_f32 v57, v56, v193, v205
	v_fma_f32 v56, v56, v192, -v204
	v_mul_f32_e32 v204, v59, v195
	v_mul_f32_e32 v205, v59, v194
	v_fma_f32 v59, v58, v195, v205
	v_fma_f32 v58, v58, v194, -v204
	v_cvt_pk_bf16_f32 v60, v60, v61
	v_cvt_pk_bf16_f32 v61, v62, v63
	v_cvt_pk_bf16_f32 v62, v56, v57
	v_cvt_pk_bf16_f32 v63, v58, v59
	global_store_dwordx4 v160, v[60:63], s[70:71]
	v_mul_f32_e32 v52, v52, v144
	v_mul_f32_e32 v53, v53, v144
	v_mul_f32_e32 v54, v54, v144
	v_mul_f32_e32 v55, v55, v144
	v_mul_f32_e32 v48, v48, v144
	v_mul_f32_e32 v49, v49, v144
	v_mul_f32_e32 v50, v50, v144
	v_mul_f32_e32 v51, v51, v144
	v_cvt_pk_bf16_f32 v52, v52, v53
	v_cvt_pk_bf16_f32 v53, v54, v55
	v_cvt_pk_bf16_f32 v54, v48, v49
	v_cvt_pk_bf16_f32 v55, v50, v51
	global_store_dwordx4 v160, v[52:55], s[70:71] offset:256
	s_waitcnt vmcnt(28)
	v_fmamk_f32 v145, v145, 0x3b000000, v207
	v_rsq_f32_e32 v145, v145
	s_add_u32 s70, s16, 0xd8000
	s_addc_u32 s71, s17, 0
	v_mul_f32_e32 v145, 0x3dd53b94, v145
	v_mul_f32_e32 v44, v44, v145
	v_mul_f32_e32 v45, v45, v145
	v_mul_f32_e32 v46, v46, v145
	v_mul_f32_e32 v47, v47, v145
	v_mul_f32_e32 v40, v40, v145
	v_mul_f32_e32 v41, v41, v145
	v_mul_f32_e32 v42, v42, v145
	v_mul_f32_e32 v43, v43, v145
	s_waitcnt vmcnt(14)
	v_mul_f32_e32 v204, v45, v197
	v_mul_f32_e32 v205, v45, v196
	v_fma_f32 v45, v44, v197, v205
	v_fma_f32 v44, v44, v196, -v204
	v_mul_f32_e32 v204, v47, v199
	v_mul_f32_e32 v205, v47, v198
	v_fma_f32 v47, v46, v199, v205
	v_fma_f32 v46, v46, v198, -v204
	v_mul_f32_e32 v204, v41, v201
	v_mul_f32_e32 v205, v41, v200
	v_fma_f32 v41, v40, v201, v205
	v_fma_f32 v40, v40, v200, -v204
	v_mul_f32_e32 v204, v43, v203
	v_mul_f32_e32 v205, v43, v202
	v_fma_f32 v43, v42, v203, v205
	v_fma_f32 v42, v42, v202, -v204
	v_cvt_pk_bf16_f32 v44, v44, v45
	v_cvt_pk_bf16_f32 v45, v46, v47
	v_cvt_pk_bf16_f32 v46, v40, v41
	v_cvt_pk_bf16_f32 v47, v42, v43
	global_store_dwordx4 v160, v[44:47], s[70:71]
	v_mul_f32_e32 v36, v36, v145
	v_mul_f32_e32 v37, v37, v145
	v_mul_f32_e32 v38, v38, v145
	v_mul_f32_e32 v39, v39, v145
	v_mul_f32_e32 v32, v32, v145
	v_mul_f32_e32 v33, v33, v145
	v_mul_f32_e32 v34, v34, v145
	v_mul_f32_e32 v35, v35, v145
	v_cvt_pk_bf16_f32 v36, v36, v37
	v_cvt_pk_bf16_f32 v37, v38, v39
	v_cvt_pk_bf16_f32 v38, v32, v33
	v_cvt_pk_bf16_f32 v39, v34, v35
	global_store_dwordx4 v160, v[36:39], s[70:71] offset:256
	s_waitcnt vmcnt(29)
	v_fmamk_f32 v146, v146, 0x3b000000, v207
	v_rsq_f32_e32 v146, v146
	s_add_u32 s70, s16, 0xf0000
	s_addc_u32 s71, s17, 0
	v_mul_f32_e32 v146, 0x3dd53b94, v146
	v_mul_f32_e32 v28, v28, v146
	v_mul_f32_e32 v29, v29, v146
	v_mul_f32_e32 v30, v30, v146
	v_mul_f32_e32 v31, v31, v146
	v_mul_f32_e32 v24, v24, v146
	v_mul_f32_e32 v25, v25, v146
	v_mul_f32_e32 v26, v26, v146
	v_mul_f32_e32 v27, v27, v146
	s_waitcnt vmcnt(14)
	v_mul_f32_e32 v204, v29, v209
	v_mul_f32_e32 v205, v29, v208
	v_fma_f32 v29, v28, v209, v205
	v_fma_f32 v28, v28, v208, -v204
	v_mul_f32_e32 v204, v31, v211
	v_mul_f32_e32 v205, v31, v210
	v_fma_f32 v31, v30, v211, v205
	v_fma_f32 v30, v30, v210, -v204
	v_mul_f32_e32 v204, v25, v217
	v_mul_f32_e32 v205, v25, v216
	v_fma_f32 v25, v24, v217, v205
	v_fma_f32 v24, v24, v216, -v204
	v_mul_f32_e32 v204, v27, v219
	v_mul_f32_e32 v205, v27, v218
	v_fma_f32 v27, v26, v219, v205
	v_fma_f32 v26, v26, v218, -v204
	v_cvt_pk_bf16_f32 v28, v28, v29
	v_cvt_pk_bf16_f32 v29, v30, v31
	v_cvt_pk_bf16_f32 v30, v24, v25
	v_cvt_pk_bf16_f32 v31, v26, v27
	global_store_dwordx4 v160, v[28:31], s[70:71]
	v_mul_f32_e32 v20, v20, v146
	v_mul_f32_e32 v21, v21, v146
	v_mul_f32_e32 v22, v22, v146
	v_mul_f32_e32 v23, v23, v146
	v_mul_f32_e32 v16, v16, v146
	v_mul_f32_e32 v17, v17, v146
	v_mul_f32_e32 v18, v18, v146
	v_mul_f32_e32 v19, v19, v146
	v_cvt_pk_bf16_f32 v20, v20, v21
	v_cvt_pk_bf16_f32 v21, v22, v23
	v_cvt_pk_bf16_f32 v22, v16, v17
	v_cvt_pk_bf16_f32 v23, v18, v19
	global_store_dwordx4 v160, v[20:23], s[70:71] offset:256
	s_waitcnt vmcnt(30)
; __device__ __forceinline__ u32x4 pack8(f32x4 v0, f32x4 v1) { u32x4 w; w.x = cvt_pk_bf16(v0[0], v0[1]); w.y = cvt_pk_bf16(v0[2], v0[3]); w.z = cvt_pk_bf16(v1[0], v1[1]); w.w = cvt_pk_bf16(v1[2], v1[3]); return w; }
;     __device__ __forceinline__ void operator()(EPI_ARGS) const {
;     ...
;             for (int m = 0; m < 4; ++m) { const int row = row0 + ai * HALF + m * 16; const float sc = rsqrtf(SSQ[row * 2] * (1.f / 512.f) + EPS) * c2;
;                 const int s = row % SB; const bool lat = s >= CTXL; const int t = s - CTXL;
; #pragma unroll
;                 for (int bj = 0; bj < 2; ++bj) { const int col0 = u.pn * BM + bj * HALF + wc * 32 + 8 * fq; const int d0 = col0 % 192;
;                     f32x4 v0 = acc[ai][bj][m][0] * sc, v1 = acc[ai][bj][m][1] * sc;
;                     if (d0 >= 128 && lat) { const float* rp = ROPE + ((size_t)t * 32 + ((d0 - 128) >> 1)) * 2; const f32x4 r0 = *(const f32x4*)rp, r1 = *(const f32x4*)(rp + 4);
;                         f32x4 o0, o1;
;                         o0[0] = v0[0] * r0[0] - v0[1] * r0[1]; o0[1] = v0[0] * r0[1] + v0[1] * r0[0]; o0[2] = v0[2] * r0[2] - v0[3] * r0[3]; o0[3] = v0[2] * r0[3] + v0[3] * r0[2];
;                         o1[0] = v1[0] * r1[0] - v1[1] * r1[1]; o1[1] = v1[0] * r1[1] + v1[1] * r1[0]; o1[2] = v1[2] * r1[2] - v1[3] * r1[3]; o1[3] = v1[2] * r1[3] + v1[3] * r1[2];
;                         v0 = o0; v1 = o1; }
;                     *(u32x4*)(Q + (size_t)row * QLD + col0) = pack8(v0, v1); }
	v_fmamk_f32 v147, v147, 0x3b000000, v207
	v_rsq_f32_e32 v147, v147
	s_add_u32 s70, s16, 0x108000
	s_addc_u32 s71, s17, 0
	v_mul_f32_e32 v147, 0x3dd53b94, v147
	v_mul_f32_e32 v12, v12, v147
	v_mul_f32_e32 v13, v13, v147
	v_mul_f32_e32 v14, v14, v147
	v_mul_f32_e32 v15, v15, v147
	v_mul_f32_e32 v8, v8, v147
	v_mul_f32_e32 v9, v9, v147
	v_mul_f32_e32 v10, v10, v147
	v_mul_f32_e32 v11, v11, v147
	s_waitcnt vmcnt(14)
	v_mul_f32_e32 v204, v13, v221
	v_mul_f32_e32 v205, v13, v220
	v_fma_f32 v13, v12, v221, v205
	v_fma_f32 v12, v12, v220, -v204
	v_mul_f32_e32 v204, v15, v223
	v_mul_f32_e32 v205, v15, v222
	v_fma_f32 v15, v14, v223, v205
	v_fma_f32 v14, v14, v222, -v204
	v_mul_f32_e32 v204, v9, v225
	v_mul_f32_e32 v205, v9, v224
	v_fma_f32 v9, v8, v225, v205
	v_fma_f32 v8, v8, v224, -v204
	v_mul_f32_e32 v204, v11, v227
	v_mul_f32_e32 v205, v11, v226
	v_fma_f32 v11, v10, v227, v205
	v_fma_f32 v10, v10, v226, -v204
	v_cvt_pk_bf16_f32 v12, v12, v13
	v_cvt_pk_bf16_f32 v13, v14, v15
	v_cvt_pk_bf16_f32 v14, v8, v9
	v_cvt_pk_bf16_f32 v15, v10, v11
	global_store_dwordx4 v160, v[12:15], s[70:71]
	v_mul_f32_e32 v4, v4, v147
	v_mul_f32_e32 v5, v5, v147
	v_mul_f32_e32 v6, v6, v147
	v_mul_f32_e32 v7, v7, v147
	v_mul_f32_e32 v0, v0, v147
	v_mul_f32_e32 v1, v1, v147
	v_mul_f32_e32 v2, v2, v147
	v_mul_f32_e32 v3, v3, v147
	v_cvt_pk_bf16_f32 v4, v4, v5
	v_cvt_pk_bf16_f32 v5, v6, v7
	v_cvt_pk_bf16_f32 v6, v0, v1
	v_cvt_pk_bf16_f32 v7, v2, v3
	global_store_dwordx4 v160, v[4:7], s[70:71] offset:256
	s_branch .Lmy_q_done
.Lmy_q_rope1:
	s_sub_i32 s36, s4, 4
	s_lshl_b32 s36, s36, 7
	s_sub_i32 s30, s30, 1
	s_lshl_b32 s30, s30, 8
	v_add_u32_e32 v205, s30, v148
	v_and_b32_e32 v204, 31, v150
	v_lshlrev_b32_e32 v205, 8, v205
	v_lshl_add_u32 v205, v204, 2, v205
	s_add_u32 s42, s20, s36
	s_addc_u32 s43, s21, 0
	global_load_dwordx4 v[152:155], v205, s[42:43]
	global_load_dwordx4 v[156:159], v205, s[42:43] offset:16
	s_add_u32 s64, s42, 0x1000
	s_addc_u32 s65, s43, 0
	global_load_dwordx4 v[164:167], v205, s[64:65]
	global_load_dwordx4 v[168:171], v205, s[64:65] offset:16
	s_add_u32 s64, s42, 0x2000
	s_addc_u32 s65, s43, 0
	global_load_dwordx4 v[172:175], v205, s[64:65]
	global_load_dwordx4 v[176:179], v205, s[64:65] offset:16
	s_add_u32 s64, s42, 0x3000
	s_addc_u32 s65, s43, 0
	global_load_dwordx4 v[180:183], v205, s[64:65]
	global_load_dwordx4 v[184:187], v205, s[64:65] offset:16
	s_add_u32 s64, s42, 0x8000
	s_addc_u32 s65, s43, 0
	global_load_dwordx4 v[188:191], v205, s[64:65]
	global_load_dwordx4 v[192:195], v205, s[64:65] offset:16
	s_add_u32 s64, s42, 0x9000
	s_addc_u32 s65, s43, 0
	global_load_dwordx4 v[196:199], v205, s[64:65]
	global_load_dwordx4 v[200:203], v205, s[64:65] offset:16
	s_add_u32 s64, s42, 0xa000
	s_addc_u32 s65, s43, 0
	global_load_dwordx4 v[208:211], v205, s[64:65]
	global_load_dwordx4 v[216:219], v205, s[64:65] offset:16
	s_add_u32 s64, s42, 0xb000
	s_addc_u32 s65, s43, 0
	global_load_dwordx4 v[220:223], v205, s[64:65]
	global_load_dwordx4 v[224:227], v205, s[64:65] offset:16
	s_waitcnt vmcnt(23)
	v_fmamk_f32 v140, v140, 0x3b000000, v207
	v_rsq_f32_e32 v140, v140
	s_nop 0
	v_mul_f32_e32 v140, 0x3dd53b94, v140
	v_mul_f32_e32 v124, v124, v140
	v_mul_f32_e32 v125, v125, v140
	v_mul_f32_e32 v126, v126, v140
	v_mul_f32_e32 v127, v127, v140
	v_mul_f32_e32 v120, v120, v140
	v_mul_f32_e32 v121, v121, v140
	v_mul_f32_e32 v122, v122, v140
	v_mul_f32_e32 v123, v123, v140
	v_cvt_pk_bf16_f32 v124, v124, v125
	v_cvt_pk_bf16_f32 v125, v126, v127
	v_cvt_pk_bf16_f32 v126, v120, v121
	v_cvt_pk_bf16_f32 v127, v122, v123
	global_store_dwordx4 v160, v[124:127], s[16:17]
	v_mul_f32_e32 v116, v116, v140
	v_mul_f32_e32 v117, v117, v140
	v_mul_f32_e32 v118, v118, v140
	v_mul_f32_e32 v119, v119, v140
	v_mul_f32_e32 v112, v112, v140
	v_mul_f32_e32 v113, v113, v140
	v_mul_f32_e32 v114, v114, v140
	v_mul_f32_e32 v115, v115, v140
	s_waitcnt vmcnt(15)
	v_mul_f32_e32 v204, v117, v153
	v_mul_f32_e32 v205, v117, v152
	v_fma_f32 v117, v116, v153, v205
	v_fma_f32 v116, v116, v152, -v204
	v_mul_f32_e32 v204, v119, v155
	v_mul_f32_e32 v205, v119, v154
	v_fma_f32 v119, v118, v155, v205
	v_fma_f32 v118, v118, v154, -v204
	v_mul_f32_e32 v204, v113, v157
	v_mul_f32_e32 v205, v113, v156
	v_fma_f32 v113, v112, v157, v205
	v_fma_f32 v112, v112, v156, -v204
	v_mul_f32_e32 v204, v115, v159
	v_mul_f32_e32 v205, v115, v158
	v_fma_f32 v115, v114, v159, v205
	v_fma_f32 v114, v114, v158, -v204
	v_cvt_pk_bf16_f32 v116, v116, v117
	v_cvt_pk_bf16_f32 v117, v118, v119
	v_cvt_pk_bf16_f32 v118, v112, v113
	v_cvt_pk_bf16_f32 v119, v114, v115
	global_store_dwordx4 v160, v[116:119], s[16:17] offset:256
	s_waitcnt vmcnt(24)
	v_fmamk_f32 v141, v141, 0x3b000000, v207
	v_rsq_f32_e32 v141, v141
	s_add_u32 s70, s16, 0x18000
	s_addc_u32 s71, s17, 0
	v_mul_f32_e32 v141, 0x3dd53b94, v141
	v_mul_f32_e32 v108, v108, v141
	v_mul_f32_e32 v109, v109, v141
	v_mul_f32_e32 v110, v110, v141
	v_mul_f32_e32 v111, v111, v141
	v_mul_f32_e32 v104, v104, v141
	v_mul_f32_e32 v105, v105, v141
	v_mul_f32_e32 v106, v106, v141
	v_mul_f32_e32 v107, v107, v141
	v_cvt_pk_bf16_f32 v108, v108, v109
	v_cvt_pk_bf16_f32 v109, v110, v111
	v_cvt_pk_bf16_f32 v110, v104, v105
	v_cvt_pk_bf16_f32 v111, v106, v107
	global_store_dwordx4 v160, v[108:111], s[70:71]
	v_mul_f32_e32 v100, v100, v141
	v_mul_f32_e32 v101, v101, v141
	v_mul_f32_e32 v102, v102, v141
	v_mul_f32_e32 v103, v103, v141
	v_mul_f32_e32 v96, v96, v141
	v_mul_f32_e32 v97, v97, v141
	v_mul_f32_e32 v98, v98, v141
	v_mul_f32_e32 v99, v99, v141
	s_waitcnt vmcnt(15)
; __device__ __forceinline__ u32x4 pack8(f32x4 v0, f32x4 v1) { u32x4 w; w.x = cvt_pk_bf16(v0[0], v0[1]); w.y = cvt_pk_bf16(v0[2], v0[3]); w.z = cvt_pk_bf16(v1[0], v1[1]); w.w = cvt_pk_bf16(v1[2], v1[3]); return w; }
;     __device__ __forceinline__ void operator()(EPI_ARGS) const {
;     ...
;             for (int m = 0; m < 4; ++m) { const int row = row0 + ai * HALF + m * 16; const float sc = rsqrtf(SSQ[row * 2] * (1.f / 512.f) + EPS) * c2;
;                 const int s = row % SB; const bool lat = s >= CTXL; const int t = s - CTXL;
; #pragma unroll
;                 for (int bj = 0; bj < 2; ++bj) { const int col0 = u.pn * BM + bj * HALF + wc * 32 + 8 * fq; const int d0 = col0 % 192;
;                     f32x4 v0 = acc[ai][bj][m][0] * sc, v1 = acc[ai][bj][m][1] * sc;
;                     if (d0 >= 128 && lat) { const float* rp = ROPE + ((size_t)t * 32 + ((d0 - 128) >> 1)) * 2; const f32x4 r0 = *(const f32x4*)rp, r1 = *(const f32x4*)(rp + 4);
;                         f32x4 o0, o1;
;                         o0[0] = v0[0] * r0[0] - v0[1] * r0[1]; o0[1] = v0[0] * r0[1] + v0[1] * r0[0]; o0[2] = v0[2] * r0[2] - v0[3] * r0[3]; o0[3] = v0[2] * r0[3] + v0[3] * r0[2];
;                         o1[0] = v1[0] * r1[0] - v1[1] * r1[1]; o1[1] = v1[0] * r1[1] + v1[1] * r1[0]; o1[2] = v1[2] * r1[2] - v1[3] * r1[3]; o1[3] = v1[2] * r1[3] + v1[3] * r1[2];
;                         v0 = o0; v1 = o1; }
;                     *(u32x4*)(Q + (size_t)row * QLD + col0) = pack8(v0, v1); }
	v_mul_f32_e32 v204, v101, v165
	v_mul_f32_e32 v205, v101, v164
	v_fma_f32 v101, v100, v165, v205
	v_fma_f32 v100, v100, v164, -v204
	v_mul_f32_e32 v204, v103, v167
	v_mul_f32_e32 v205, v103, v166
	v_fma_f32 v103, v102, v167, v205
	v_fma_f32 v102, v102, v166, -v204
	v_mul_f32_e32 v204, v97, v169
	v_mul_f32_e32 v205, v97, v168
	v_fma_f32 v97, v96, v169, v205
	v_fma_f32 v96, v96, v168, -v204
	v_mul_f32_e32 v204, v99, v171
	v_mul_f32_e32 v205, v99, v170
	v_fma_f32 v99, v98, v171, v205
	v_fma_f32 v98, v98, v170, -v204
	v_cvt_pk_bf16_f32 v100, v100, v101
	v_cvt_pk_bf16_f32 v101, v102, v103
	v_cvt_pk_bf16_f32 v102, v96, v97
	v_cvt_pk_bf16_f32 v103, v98, v99
	global_store_dwordx4 v160, v[100:103], s[70:71] offset:256
	s_waitcnt vmcnt(25)
	v_fmamk_f32 v142, v142, 0x3b000000, v207
	v_rsq_f32_e32 v142, v142
	s_add_u32 s70, s16, 0x30000
	s_addc_u32 s71, s17, 0
	v_mul_f32_e32 v142, 0x3dd53b94, v142
	v_mul_f32_e32 v92, v92, v142
	v_mul_f32_e32 v93, v93, v142
	v_mul_f32_e32 v94, v94, v142
	v_mul_f32_e32 v95, v95, v142
	v_mul_f32_e32 v88, v88, v142
	v_mul_f32_e32 v89, v89, v142
	v_mul_f32_e32 v90, v90, v142
	v_mul_f32_e32 v91, v91, v142
	v_cvt_pk_bf16_f32 v92, v92, v93
	v_cvt_pk_bf16_f32 v93, v94, v95
	v_cvt_pk_bf16_f32 v94, v88, v89
	v_cvt_pk_bf16_f32 v95, v90, v91
	global_store_dwordx4 v160, v[92:95], s[70:71]
	v_mul_f32_e32 v84, v84, v142
	v_mul_f32_e32 v85, v85, v142
	v_mul_f32_e32 v86, v86, v142
	v_mul_f32_e32 v87, v87, v142
	v_mul_f32_e32 v80, v80, v142
	v_mul_f32_e32 v81, v81, v142
	v_mul_f32_e32 v82, v82, v142
	v_mul_f32_e32 v83, v83, v142
	s_waitcnt vmcnt(15)
	v_mul_f32_e32 v204, v85, v173
	v_mul_f32_e32 v205, v85, v172
	v_fma_f32 v85, v84, v173, v205
	v_fma_f32 v84, v84, v172, -v204
	v_mul_f32_e32 v204, v87, v175
	v_mul_f32_e32 v205, v87, v174
	v_fma_f32 v87, v86, v175, v205
	v_fma_f32 v86, v86, v174, -v204
	v_mul_f32_e32 v204, v81, v177
	v_mul_f32_e32 v205, v81, v176
	v_fma_f32 v81, v80, v177, v205
	v_fma_f32 v80, v80, v176, -v204
	v_mul_f32_e32 v204, v83, v179
	v_mul_f32_e32 v205, v83, v178
	v_fma_f32 v83, v82, v179, v205
	v_fma_f32 v82, v82, v178, -v204
	v_cvt_pk_bf16_f32 v84, v84, v85
	v_cvt_pk_bf16_f32 v85, v86, v87
	v_cvt_pk_bf16_f32 v86, v80, v81
	v_cvt_pk_bf16_f32 v87, v82, v83
	global_store_dwordx4 v160, v[84:87], s[70:71] offset:256
	s_waitcnt vmcnt(26)
	v_fmamk_f32 v143, v143, 0x3b000000, v207
	v_rsq_f32_e32 v143, v143
	s_add_u32 s70, s16, 0x48000
	s_addc_u32 s71, s17, 0
	v_mul_f32_e32 v143, 0x3dd53b94, v143
	v_mul_f32_e32 v76, v76, v143
	v_mul_f32_e32 v77, v77, v143
	v_mul_f32_e32 v78, v78, v143
	v_mul_f32_e32 v79, v79, v143
	v_mul_f32_e32 v72, v72, v143
	v_mul_f32_e32 v73, v73, v143
	v_mul_f32_e32 v74, v74, v143
	v_mul_f32_e32 v75, v75, v143
	v_cvt_pk_bf16_f32 v76, v76, v77
	v_cvt_pk_bf16_f32 v77, v78, v79
	v_cvt_pk_bf16_f32 v78, v72, v73
	v_cvt_pk_bf16_f32 v79, v74, v75
	global_store_dwordx4 v160, v[76:79], s[70:71]
	v_mul_f32_e32 v68, v68, v143
	v_mul_f32_e32 v69, v69, v143
	v_mul_f32_e32 v70, v70, v143
	v_mul_f32_e32 v71, v71, v143
	v_mul_f32_e32 v64, v64, v143
	v_mul_f32_e32 v65, v65, v143
	v_mul_f32_e32 v66, v66, v143
	v_mul_f32_e32 v67, v67, v143
	s_waitcnt vmcnt(15)
	v_mul_f32_e32 v204, v69, v181
	v_mul_f32_e32 v205, v69, v180
	v_fma_f32 v69, v68, v181, v205
	v_fma_f32 v68, v68, v180, -v204
	v_mul_f32_e32 v204, v71, v183
	v_mul_f32_e32 v205, v71, v182
	v_fma_f32 v71, v70, v183, v205
	v_fma_f32 v70, v70, v182, -v204
	v_mul_f32_e32 v204, v65, v185
	v_mul_f32_e32 v205, v65, v184
	v_fma_f32 v65, v64, v185, v205
	v_fma_f32 v64, v64, v184, -v204
	v_mul_f32_e32 v204, v67, v187
	v_mul_f32_e32 v205, v67, v186
	v_fma_f32 v67, v66, v187, v205
	v_fma_f32 v66, v66, v186, -v204
	v_cvt_pk_bf16_f32 v68, v68, v69
	v_cvt_pk_bf16_f32 v69, v70, v71
	v_cvt_pk_bf16_f32 v70, v64, v65
	v_cvt_pk_bf16_f32 v71, v66, v67
	global_store_dwordx4 v160, v[68:71], s[70:71] offset:256
	s_waitcnt vmcnt(27)
	v_fmamk_f32 v144, v144, 0x3b000000, v207
	v_rsq_f32_e32 v144, v144
	s_add_u32 s70, s16, 0xc0000
	s_addc_u32 s71, s17, 0
	v_mul_f32_e32 v144, 0x3dd53b94, v144
	v_mul_f32_e32 v60, v60, v144
	v_mul_f32_e32 v61, v61, v144
	v_mul_f32_e32 v62, v62, v144
	v_mul_f32_e32 v63, v63, v144
	v_mul_f32_e32 v56, v56, v144
	v_mul_f32_e32 v57, v57, v144
	v_mul_f32_e32 v58, v58, v144
	v_mul_f32_e32 v59, v59, v144
	v_cvt_pk_bf16_f32 v60, v60, v61
	v_cvt_pk_bf16_f32 v61, v62, v63
	v_cvt_pk_bf16_f32 v62, v56, v57
	v_cvt_pk_bf16_f32 v63, v58, v59
	global_store_dwordx4 v160, v[60:63], s[70:71]
	v_mul_f32_e32 v52, v52, v144
	v_mul_f32_e32 v53, v53, v144
	v_mul_f32_e32 v54, v54, v144
	v_mul_f32_e32 v55, v55, v144
	v_mul_f32_e32 v48, v48, v144
	v_mul_f32_e32 v49, v49, v144
	v_mul_f32_e32 v50, v50, v144
	v_mul_f32_e32 v51, v51, v144
	s_waitcnt vmcnt(15)
	v_mul_f32_e32 v204, v53, v189
	v_mul_f32_e32 v205, v53, v188
	v_fma_f32 v53, v52, v189, v205
	v_fma_f32 v52, v52, v188, -v204
	v_mul_f32_e32 v204, v55, v191
	v_mul_f32_e32 v205, v55, v190
	v_fma_f32 v55, v54, v191, v205
	v_fma_f32 v54, v54, v190, -v204
	v_mul_f32_e32 v204, v49, v193
	v_mul_f32_e32 v205, v49, v192
	v_fma_f32 v49, v48, v193, v205
	v_fma_f32 v48, v48, v192, -v204
	v_mul_f32_e32 v204, v51, v195
	v_mul_f32_e32 v205, v51, v194
	v_fma_f32 v51, v50, v195, v205
	v_fma_f32 v50, v50, v194, -v204
	v_cvt_pk_bf16_f32 v52, v52, v53
	v_cvt_pk_bf16_f32 v53, v54, v55
	v_cvt_pk_bf16_f32 v54, v48, v49
	v_cvt_pk_bf16_f32 v55, v50, v51
	global_store_dwordx4 v160, v[52:55], s[70:71] offset:256
	s_waitcnt vmcnt(28)
; #define PG8_BAR __builtin_amdgcn_s_barrier()
; __device__ __forceinline__ u32x4 pack8(f32x4 v0, f32x4 v1) { u32x4 w; w.x = cvt_pk_bf16(v0[0], v0[1]); w.y = cvt_pk_bf16(v0[2], v0[3]); w.z = cvt_pk_bf16(v1[0], v1[1]); w.w = cvt_pk_bf16(v1[2], v1[3]); return w; }
; template <class Epi, bool HAS_MID>
; __device__ __forceinline__ void gemm_phase(LAS unsigned char* lds, const Gemm g, const Sched& S, const Epi& E) {
;     ...
;         if (wr == 0) PG8_BAR;
;         E(acc, cur, wr, wc, fr, fq);
;         if (!has_next) break;
; #pragma unroll
;         for (int a = 0; a < 2; ++a)
; #pragma unroll
;             for (int b = 0; b < 2; ++b)
; #pragma unroll
;                 for (int m = 0; m < 4; ++m)
; #pragma unroll
;                     for (int n = 0; n < 2; ++n) acc[a][b][m][n] = (f32x4){0.f, 0.f, 0.f, 0.f};
;         cur = nxt; cA = nA; cB = nB; ++ui;
;         if (wr == 1) PG8_BAR;
;     }
;     __device__ __forceinline__ void operator()(EPI_ARGS) const {
;     ...
;             for (int m = 0; m < 4; ++m) { const int row = row0 + ai * HALF + m * 16; const float sc = rsqrtf(SSQ[row * 2] * (1.f / 512.f) + EPS) * c2;
;                 const int s = row % SB; const bool lat = s >= CTXL; const int t = s - CTXL;
; #pragma unroll
;                 for (int bj = 0; bj < 2; ++bj) { const int col0 = u.pn * BM + bj * HALF + wc * 32 + 8 * fq; const int d0 = col0 % 192;
;                     f32x4 v0 = acc[ai][bj][m][0] * sc, v1 = acc[ai][bj][m][1] * sc;
;                     if (d0 >= 128 && lat) { const float* rp = ROPE + ((size_t)t * 32 + ((d0 - 128) >> 1)) * 2; const f32x4 r0 = *(const f32x4*)rp, r1 = *(const f32x4*)(rp + 4);
;                         f32x4 o0, o1;
;                         o0[0] = v0[0] * r0[0] - v0[1] * r0[1]; o0[1] = v0[0] * r0[1] + v0[1] * r0[0]; o0[2] = v0[2] * r0[2] - v0[3] * r0[3]; o0[3] = v0[2] * r0[3] + v0[3] * r0[2];
;                         o1[0] = v1[0] * r1[0] - v1[1] * r1[1]; o1[1] = v1[0] * r1[1] + v1[1] * r1[0]; o1[2] = v1[2] * r1[2] - v1[3] * r1[3]; o1[3] = v1[2] * r1[3] + v1[3] * r1[2];
;                         v0 = o0; v1 = o1; }
;                     *(u32x4*)(Q + (size_t)row * QLD + col0) = pack8(v0, v1); }
;                 asm volatile("" ::: "memory"); }
	v_fmamk_f32 v145, v145, 0x3b000000, v207
	v_rsq_f32_e32 v145, v145
	s_add_u32 s70, s16, 0xd8000
	s_addc_u32 s71, s17, 0
	v_mul_f32_e32 v145, 0x3dd53b94, v145
	v_mul_f32_e32 v44, v44, v145
	v_mul_f32_e32 v45, v45, v145
	v_mul_f32_e32 v46, v46, v145
	v_mul_f32_e32 v47, v47, v145
	v_mul_f32_e32 v40, v40, v145
	v_mul_f32_e32 v41, v41, v145
	v_mul_f32_e32 v42, v42, v145
	v_mul_f32_e32 v43, v43, v145
	v_cvt_pk_bf16_f32 v44, v44, v45
	v_cvt_pk_bf16_f32 v45, v46, v47
	v_cvt_pk_bf16_f32 v46, v40, v41
	v_cvt_pk_bf16_f32 v47, v42, v43
	global_store_dwordx4 v160, v[44:47], s[70:71]
	v_mul_f32_e32 v36, v36, v145
	v_mul_f32_e32 v37, v37, v145
	v_mul_f32_e32 v38, v38, v145
	v_mul_f32_e32 v39, v39, v145
	v_mul_f32_e32 v32, v32, v145
	v_mul_f32_e32 v33, v33, v145
	v_mul_f32_e32 v34, v34, v145
	v_mul_f32_e32 v35, v35, v145
	s_waitcnt vmcnt(15)
	v_mul_f32_e32 v204, v37, v197
	v_mul_f32_e32 v205, v37, v196
	v_fma_f32 v37, v36, v197, v205
	v_fma_f32 v36, v36, v196, -v204
	v_mul_f32_e32 v204, v39, v199
	v_mul_f32_e32 v205, v39, v198
	v_fma_f32 v39, v38, v199, v205
	v_fma_f32 v38, v38, v198, -v204
	v_mul_f32_e32 v204, v33, v201
	v_mul_f32_e32 v205, v33, v200
	v_fma_f32 v33, v32, v201, v205
	v_fma_f32 v32, v32, v200, -v204
	v_mul_f32_e32 v204, v35, v203
	v_mul_f32_e32 v205, v35, v202
	v_fma_f32 v35, v34, v203, v205
	v_fma_f32 v34, v34, v202, -v204
	v_cvt_pk_bf16_f32 v36, v36, v37
	v_cvt_pk_bf16_f32 v37, v38, v39
	v_cvt_pk_bf16_f32 v38, v32, v33
	v_cvt_pk_bf16_f32 v39, v34, v35
	global_store_dwordx4 v160, v[36:39], s[70:71] offset:256
	s_waitcnt vmcnt(29)
	v_fmamk_f32 v146, v146, 0x3b000000, v207
	v_rsq_f32_e32 v146, v146
	s_add_u32 s70, s16, 0xf0000
	s_addc_u32 s71, s17, 0
	v_mul_f32_e32 v146, 0x3dd53b94, v146
	v_mul_f32_e32 v28, v28, v146
	v_mul_f32_e32 v29, v29, v146
	v_mul_f32_e32 v30, v30, v146
	v_mul_f32_e32 v31, v31, v146
	v_mul_f32_e32 v24, v24, v146
	v_mul_f32_e32 v25, v25, v146
	v_mul_f32_e32 v26, v26, v146
	v_mul_f32_e32 v27, v27, v146
	v_cvt_pk_bf16_f32 v28, v28, v29
	v_cvt_pk_bf16_f32 v29, v30, v31
	v_cvt_pk_bf16_f32 v30, v24, v25
	v_cvt_pk_bf16_f32 v31, v26, v27
	global_store_dwordx4 v160, v[28:31], s[70:71]
	v_mul_f32_e32 v20, v20, v146
	v_mul_f32_e32 v21, v21, v146
	v_mul_f32_e32 v22, v22, v146
	v_mul_f32_e32 v23, v23, v146
	v_mul_f32_e32 v16, v16, v146
	v_mul_f32_e32 v17, v17, v146
	v_mul_f32_e32 v18, v18, v146
	v_mul_f32_e32 v19, v19, v146
	s_waitcnt vmcnt(15)
	v_mul_f32_e32 v204, v21, v209
	v_mul_f32_e32 v205, v21, v208
	v_fma_f32 v21, v20, v209, v205
	v_fma_f32 v20, v20, v208, -v204
	v_mul_f32_e32 v204, v23, v211
	v_mul_f32_e32 v205, v23, v210
	v_fma_f32 v23, v22, v211, v205
	v_fma_f32 v22, v22, v210, -v204
	v_mul_f32_e32 v204, v17, v217
	v_mul_f32_e32 v205, v17, v216
	v_fma_f32 v17, v16, v217, v205
	v_fma_f32 v16, v16, v216, -v204
	v_mul_f32_e32 v204, v19, v219
	v_mul_f32_e32 v205, v19, v218
	v_fma_f32 v19, v18, v219, v205
	v_fma_f32 v18, v18, v218, -v204
	v_cvt_pk_bf16_f32 v20, v20, v21
	v_cvt_pk_bf16_f32 v21, v22, v23
	v_cvt_pk_bf16_f32 v22, v16, v17
	v_cvt_pk_bf16_f32 v23, v18, v19
	global_store_dwordx4 v160, v[20:23], s[70:71] offset:256
	s_waitcnt vmcnt(30)
	v_fmamk_f32 v147, v147, 0x3b000000, v207
	v_rsq_f32_e32 v147, v147
	s_add_u32 s70, s16, 0x108000
	s_addc_u32 s71, s17, 0
	v_mul_f32_e32 v147, 0x3dd53b94, v147
	v_mul_f32_e32 v12, v12, v147
	v_mul_f32_e32 v13, v13, v147
	v_mul_f32_e32 v14, v14, v147
	v_mul_f32_e32 v15, v15, v147
	v_mul_f32_e32 v8, v8, v147
	v_mul_f32_e32 v9, v9, v147
	v_mul_f32_e32 v10, v10, v147
	v_mul_f32_e32 v11, v11, v147
	v_cvt_pk_bf16_f32 v12, v12, v13
	v_cvt_pk_bf16_f32 v13, v14, v15
	v_cvt_pk_bf16_f32 v14, v8, v9
	v_cvt_pk_bf16_f32 v15, v10, v11
	global_store_dwordx4 v160, v[12:15], s[70:71]
	v_mul_f32_e32 v4, v4, v147
	v_mul_f32_e32 v5, v5, v147
	v_mul_f32_e32 v6, v6, v147
	v_mul_f32_e32 v7, v7, v147
	v_mul_f32_e32 v0, v0, v147
	v_mul_f32_e32 v1, v1, v147
	v_mul_f32_e32 v2, v2, v147
	v_mul_f32_e32 v3, v3, v147
	s_waitcnt vmcnt(15)
	v_mul_f32_e32 v204, v5, v221
	v_mul_f32_e32 v205, v5, v220
	v_fma_f32 v5, v4, v221, v205
	v_fma_f32 v4, v4, v220, -v204
	v_mul_f32_e32 v204, v7, v223
	v_mul_f32_e32 v205, v7, v222
	v_fma_f32 v7, v6, v223, v205
	v_fma_f32 v6, v6, v222, -v204
	v_mul_f32_e32 v204, v1, v225
	v_mul_f32_e32 v205, v1, v224
	v_fma_f32 v1, v0, v225, v205
	v_fma_f32 v0, v0, v224, -v204
	v_mul_f32_e32 v204, v3, v227
	v_mul_f32_e32 v205, v3, v226
	v_fma_f32 v3, v2, v227, v205
	v_fma_f32 v2, v2, v226, -v204
	v_cvt_pk_bf16_f32 v4, v4, v5
	v_cvt_pk_bf16_f32 v5, v6, v7
	v_cvt_pk_bf16_f32 v6, v0, v1
	v_cvt_pk_bf16_f32 v7, v2, v3
	global_store_dwordx4 v160, v[4:7], s[70:71] offset:256
.Lmy_q_done:
	s_and_b64 vcc, exec, s[2:3]
	s_mov_b64 s[2:3], -1
	s_cbranch_vccnz .LBB0_1168
	s_andn2_b64 vcc, exec, s[14:15]
	s_cbranch_vccnz .LBB0_1167
	s_barrier
	s_branch .LBB0_1167

; __device__ __forceinline__ int get_tid() { int t = __builtin_amdgcn_workitem_id_x(); asm volatile("" : "+v"(t)); return t; }
; __device__ __forceinline__ u32x4 pack8(f32x4 v0, f32x4 v1) { u32x4 w; w.x = cvt_pk_bf16(v0[0], v0[1]); w.y = cvt_pk_bf16(v0[2], v0[3]); w.z = cvt_pk_bf16(v1[0], v1[1]); w.w = cvt_pk_bf16(v1[2], v1[3]); return w; }
;     __device__ __forceinline__ void operator()(EPI_ARGS) const {
;         const int row0 = u.pm * BM + wr * 64 + fr; const int cw = wc * 32 + 8 * fq;
; #pragma unroll
;         for (int ai = 0; ai < 2; ++ai)
; #pragma unroll
;             for (int m = 0; m < 4; ++m) { const int row = row0 + ai * HALF + m * 16; const float sc = rsqrtf(SSQ[row * 2 + 1] * (1.f / 512.f) + EPS);
;                 *(u32x4*)(KB + (size_t)row * KLD + u.pn * 192 + cw) = pack8(acc[ai][0][m][0] * sc, acc[ai][0][m][1] * sc);
;                 *(u32x4*)(VB + (size_t)row * VLD + u.pn * 128 + cw) = pack8(acc[ai][1][m][0] * sc, acc[ai][1][m][1] * sc);
;                 asm volatile("" ::: "memory"); }
;         { const int tid = get_tid(), row = u.pm * BM + (tid >> 1), half = tid & 1; const int s = row % SB; const bool lat = s >= CTXL; const int t = s - CTXL;
;           const float* kr = MISC + (size_t)row * MISC_LD + 32 + half * 32; bf16_t* dst = KB + (size_t)row * KLD + u.pn * 192 + 128 + half * 32;
; #pragma unroll
;           for (int c = 0; c < 4; ++c) { f32x4 v0 = *(const f32x4*)(kr + c * 8), v1 = *(const f32x4*)(kr + c * 8 + 4);
;               if (lat) { const float* rp = ROPE + ((size_t)t * 32 + half * 16 + c * 4) * 2; const f32x4 r0 = *(const f32x4*)rp, r1 = *(const f32x4*)(rp + 4);
;                   f32x4 o0, o1;
;                   o0[0] = v0[0] * r0[0] - v0[1] * r0[1]; o0[1] = v0[0] * r0[1] + v0[1] * r0[0]; o0[2] = v0[2] * r0[2] - v0[3] * r0[3]; o0[3] = v0[2] * r0[3] + v0[3] * r0[2];
;                   o1[0] = v1[0] * r1[0] - v1[1] * r1[1]; o1[1] = v1[0] * r1[1] + v1[1] * r1[0]; o1[2] = v1[2] * r1[2] - v1[3] * r1[3]; o1[3] = v1[2] * r1[3] + v1[3] * r1[2];
;                   v0 = o0; v1 = o1; }
;               *(u32x4*)(dst + c * 8) = pack8(v0, v1); asm volatile("" ::: "memory"); } }
.LBB0_1228:
	v_lshl_add_u32 v225, s35, 8, v142
	v_lshlrev_b32_e32 v227, 3, v225
	global_load_dword v140, v227, s[18:19] offset:4
	global_load_dword v141, v227, s[18:19] offset:132
	global_load_dword v145, v227, s[18:19] offset:260
	global_load_dword v146, v227, s[18:19] offset:388
	global_load_dword v147, v227, s[18:19] offset:1028
	global_load_dword v204, v227, s[18:19] offset:1156
	global_load_dword v205, v227, s[18:19] offset:1284
	global_load_dword v224, v227, s[18:19] offset:1412
	v_lshrrev_b32_e32 v216, 1, v206
	v_and_b32_e32 v217, 1, v206
	v_lshl_add_u32 v218, s35, 8, v216
	v_mul_u32_u24_e32 v180, 0x180, v218
	v_lshl_add_u32 v180, v217, 7, v180
	s_add_u32 s4, s6, 0x300080
	s_addc_u32 s5, s7, 0
	global_load_dwordx4 v[148:151], v180, s[4:5]
	global_load_dwordx4 v[152:155], v180, s[4:5] offset:16
	global_load_dwordx4 v[156:159], v180, s[4:5] offset:32
	global_load_dwordx4 v[164:167], v180, s[4:5] offset:48
	global_load_dwordx4 v[168:171], v180, s[4:5] offset:64
	global_load_dwordx4 v[172:175], v180, s[4:5] offset:80
	global_load_dwordx4 v[176:179], v180, s[4:5] offset:96
	global_load_dwordx4 v[180:183], v180, s[4:5] offset:112
	s_mul_hi_i32 s30, s35, 0x38e38e39
	s_lshr_b32 s36, s30, 31
	s_ashr_i32 s30, s30, 1
	s_add_i32 s30, s30, s36
	s_mul_i32 s30, s30, 9
	s_sub_i32 s30, s35, s30
	s_mul_i32 s36, s40, 0x180
	s_add_u32 s70, s14, s36
	s_addc_u32 s71, s15, 0
	s_lshl_b32 s36, s40, 8
	s_add_u32 s72, s16, s36
	s_addc_u32 s73, s17, 0
	v_mul_u32_u24_e32 v226, 0x1800, v225
	v_lshlrev_b32_e32 v225, 12, v225
	v_add_u32_e32 v226, v226, v160
	v_add_u32_e32 v225, v225, v160
	v_mul_u32_u24_e32 v227, 0x1800, v218
	v_lshl_add_u32 v227, v217, 6, v227
	s_cmp_eq_u32 s30, 0
	s_cbranch_scc1 .Lmy_kv_nolat_a
	s_sub_i32 s25, s30, 1
	s_lshl_b32 s25, s25, 8
	v_add_u32_e32 v220, s25, v216
	v_lshlrev_b32_e32 v220, 8, v220
	v_lshl_add_u32 v220, v217, 7, v220
	global_load_dwordx4 v[184:187], v220, s[20:21]
	global_load_dwordx4 v[188:191], v220, s[20:21] offset:16
	global_load_dwordx4 v[192:195], v220, s[20:21] offset:32
	global_load_dwordx4 v[196:199], v220, s[20:21] offset:48
	global_load_dwordx4 v[200:203], v220, s[20:21] offset:64
	global_load_dwordx4 v[208:211], v220, s[20:21] offset:80
	global_load_dwordx4 v[216:219], v220, s[20:21] offset:96
	global_load_dwordx4 v[220:223], v220, s[20:21] offset:112
.Lmy_kv_nolat_a:
	s_waitcnt vmcnt(15)
	v_fmamk_f32 v140, v140, 0x3b000000, v207
	v_rsq_f32_e32 v140, v140
	s_nop 0
	v_mul_f32_e32 v124, v124, v140
	v_mul_f32_e32 v125, v125, v140
	v_mul_f32_e32 v126, v126, v140
	v_mul_f32_e32 v127, v127, v140
	v_mul_f32_e32 v120, v120, v140
	v_mul_f32_e32 v121, v121, v140
	v_mul_f32_e32 v122, v122, v140
	v_mul_f32_e32 v123, v123, v140
	v_cvt_pk_bf16_f32 v124, v124, v125
	v_cvt_pk_bf16_f32 v125, v126, v127
	v_cvt_pk_bf16_f32 v126, v120, v121
	v_cvt_pk_bf16_f32 v127, v122, v123
	global_store_dwordx4 v226, v[124:127], s[70:71]
	v_mul_f32_e32 v116, v116, v140
	v_mul_f32_e32 v117, v117, v140
	v_mul_f32_e32 v118, v118, v140
	v_mul_f32_e32 v119, v119, v140
	v_mul_f32_e32 v112, v112, v140
	v_mul_f32_e32 v113, v113, v140
	v_mul_f32_e32 v114, v114, v140
	v_mul_f32_e32 v115, v115, v140
	v_cvt_pk_bf16_f32 v116, v116, v117
	v_cvt_pk_bf16_f32 v117, v118, v119
	v_cvt_pk_bf16_f32 v118, v112, v113
	v_cvt_pk_bf16_f32 v119, v114, v115
	global_store_dwordx4 v225, v[116:119], s[72:73]
	s_waitcnt vmcnt(16)
	v_fmamk_f32 v141, v141, 0x3b000000, v207
	v_rsq_f32_e32 v141, v141
	s_add_u32 s64, s70, 0x18000
	s_addc_u32 s65, s71, 0
	s_add_u32 s74, s72, 0x10000
	s_addc_u32 s75, s73, 0
	v_mul_f32_e32 v108, v108, v141
	v_mul_f32_e32 v109, v109, v141
	v_mul_f32_e32 v110, v110, v141
	v_mul_f32_e32 v111, v111, v141
	v_mul_f32_e32 v104, v104, v141
	v_mul_f32_e32 v105, v105, v141
	v_mul_f32_e32 v106, v106, v141
	v_mul_f32_e32 v107, v107, v141
	v_cvt_pk_bf16_f32 v108, v108, v109
	v_cvt_pk_bf16_f32 v109, v110, v111
	v_cvt_pk_bf16_f32 v110, v104, v105
	v_cvt_pk_bf16_f32 v111, v106, v107
	global_store_dwordx4 v226, v[108:111], s[64:65]
	v_mul_f32_e32 v100, v100, v141
	v_mul_f32_e32 v101, v101, v141
	v_mul_f32_e32 v102, v102, v141
	v_mul_f32_e32 v103, v103, v141
	v_mul_f32_e32 v96, v96, v141
	v_mul_f32_e32 v97, v97, v141
	v_mul_f32_e32 v98, v98, v141
	v_mul_f32_e32 v99, v99, v141
	v_cvt_pk_bf16_f32 v100, v100, v101
	v_cvt_pk_bf16_f32 v101, v102, v103
	v_cvt_pk_bf16_f32 v102, v96, v97
	v_cvt_pk_bf16_f32 v103, v98, v99
	global_store_dwordx4 v225, v[100:103], s[74:75]
	s_waitcnt vmcnt(17)
	v_fmamk_f32 v145, v145, 0x3b000000, v207
	v_rsq_f32_e32 v145, v145
	s_add_u32 s64, s70, 0x30000
	s_addc_u32 s65, s71, 0
	s_add_u32 s74, s72, 0x20000
	s_addc_u32 s75, s73, 0
	v_mul_f32_e32 v92, v92, v145
	v_mul_f32_e32 v93, v93, v145
	v_mul_f32_e32 v94, v94, v145
	v_mul_f32_e32 v95, v95, v145
	v_mul_f32_e32 v88, v88, v145
	v_mul_f32_e32 v89, v89, v145
	v_mul_f32_e32 v90, v90, v145
	v_mul_f32_e32 v91, v91, v145
	v_cvt_pk_bf16_f32 v92, v92, v93
	v_cvt_pk_bf16_f32 v93, v94, v95
	v_cvt_pk_bf16_f32 v94, v88, v89
	v_cvt_pk_bf16_f32 v95, v90, v91
	global_store_dwordx4 v226, v[92:95], s[64:65]
	v_mul_f32_e32 v84, v84, v145
	v_mul_f32_e32 v85, v85, v145
	v_mul_f32_e32 v86, v86, v145
	v_mul_f32_e32 v87, v87, v145
	v_mul_f32_e32 v80, v80, v145
	v_mul_f32_e32 v81, v81, v145
	v_mul_f32_e32 v82, v82, v145
	v_mul_f32_e32 v83, v83, v145
	v_cvt_pk_bf16_f32 v84, v84, v85
	v_cvt_pk_bf16_f32 v85, v86, v87
	v_cvt_pk_bf16_f32 v86, v80, v81
	v_cvt_pk_bf16_f32 v87, v82, v83
	global_store_dwordx4 v225, v[84:87], s[74:75]
	s_waitcnt vmcnt(18)
; __device__ __forceinline__ u32x4 pack8(f32x4 v0, f32x4 v1) { u32x4 w; w.x = cvt_pk_bf16(v0[0], v0[1]); w.y = cvt_pk_bf16(v0[2], v0[3]); w.z = cvt_pk_bf16(v1[0], v1[1]); w.w = cvt_pk_bf16(v1[2], v1[3]); return w; }
;     __device__ __forceinline__ void operator()(EPI_ARGS) const {
;         const int row0 = u.pm * BM + wr * 64 + fr; const int cw = wc * 32 + 8 * fq;
; #pragma unroll
;         for (int ai = 0; ai < 2; ++ai)
; #pragma unroll
;             for (int m = 0; m < 4; ++m) { const int row = row0 + ai * HALF + m * 16; const float sc = rsqrtf(SSQ[row * 2 + 1] * (1.f / 512.f) + EPS);
;                 *(u32x4*)(KB + (size_t)row * KLD + u.pn * 192 + cw) = pack8(acc[ai][0][m][0] * sc, acc[ai][0][m][1] * sc);
;                 *(u32x4*)(VB + (size_t)row * VLD + u.pn * 128 + cw) = pack8(acc[ai][1][m][0] * sc, acc[ai][1][m][1] * sc);
;                 asm volatile("" ::: "memory"); }
	v_fmamk_f32 v146, v146, 0x3b000000, v207
	v_rsq_f32_e32 v146, v146
	s_add_u32 s64, s70, 0x48000
	s_addc_u32 s65, s71, 0
	s_add_u32 s74, s72, 0x30000
	s_addc_u32 s75, s73, 0
	v_mul_f32_e32 v76, v76, v146
	v_mul_f32_e32 v77, v77, v146
	v_mul_f32_e32 v78, v78, v146
	v_mul_f32_e32 v79, v79, v146
	v_mul_f32_e32 v72, v72, v146
	v_mul_f32_e32 v73, v73, v146
	v_mul_f32_e32 v74, v74, v146
	v_mul_f32_e32 v75, v75, v146
	v_cvt_pk_bf16_f32 v76, v76, v77
	v_cvt_pk_bf16_f32 v77, v78, v79
	v_cvt_pk_bf16_f32 v78, v72, v73
	v_cvt_pk_bf16_f32 v79, v74, v75
	global_store_dwordx4 v226, v[76:79], s[64:65]
	v_mul_f32_e32 v68, v68, v146
	v_mul_f32_e32 v69, v69, v146
	v_mul_f32_e32 v70, v70, v146
	v_mul_f32_e32 v71, v71, v146
	v_mul_f32_e32 v64, v64, v146
	v_mul_f32_e32 v65, v65, v146
	v_mul_f32_e32 v66, v66, v146
	v_mul_f32_e32 v67, v67, v146
	v_cvt_pk_bf16_f32 v68, v68, v69
	v_cvt_pk_bf16_f32 v69, v70, v71
	v_cvt_pk_bf16_f32 v70, v64, v65
	v_cvt_pk_bf16_f32 v71, v66, v67
	global_store_dwordx4 v225, v[68:71], s[74:75]
	s_waitcnt vmcnt(19)
	v_fmamk_f32 v147, v147, 0x3b000000, v207
	v_rsq_f32_e32 v147, v147
	s_add_u32 s64, s70, 0xc0000
	s_addc_u32 s65, s71, 0
	s_add_u32 s74, s72, 0x80000
	s_addc_u32 s75, s73, 0
	v_mul_f32_e32 v60, v60, v147
	v_mul_f32_e32 v61, v61, v147
	v_mul_f32_e32 v62, v62, v147
	v_mul_f32_e32 v63, v63, v147
	v_mul_f32_e32 v56, v56, v147
	v_mul_f32_e32 v57, v57, v147
	v_mul_f32_e32 v58, v58, v147
	v_mul_f32_e32 v59, v59, v147
	v_cvt_pk_bf16_f32 v60, v60, v61
	v_cvt_pk_bf16_f32 v61, v62, v63
	v_cvt_pk_bf16_f32 v62, v56, v57
	v_cvt_pk_bf16_f32 v63, v58, v59
	global_store_dwordx4 v226, v[60:63], s[64:65]
	v_mul_f32_e32 v52, v52, v147
	v_mul_f32_e32 v53, v53, v147
	v_mul_f32_e32 v54, v54, v147
	v_mul_f32_e32 v55, v55, v147
	v_mul_f32_e32 v48, v48, v147
	v_mul_f32_e32 v49, v49, v147
	v_mul_f32_e32 v50, v50, v147
	v_mul_f32_e32 v51, v51, v147
	v_cvt_pk_bf16_f32 v52, v52, v53
	v_cvt_pk_bf16_f32 v53, v54, v55
	v_cvt_pk_bf16_f32 v54, v48, v49
	v_cvt_pk_bf16_f32 v55, v50, v51
	global_store_dwordx4 v225, v[52:55], s[74:75]
	s_waitcnt vmcnt(20)
	v_fmamk_f32 v204, v204, 0x3b000000, v207
	v_rsq_f32_e32 v204, v204
	s_add_u32 s64, s70, 0xd8000
	s_addc_u32 s65, s71, 0
	s_add_u32 s74, s72, 0x90000
	s_addc_u32 s75, s73, 0
	v_mul_f32_e32 v44, v44, v204
	v_mul_f32_e32 v45, v45, v204
	v_mul_f32_e32 v46, v46, v204
	v_mul_f32_e32 v47, v47, v204
	v_mul_f32_e32 v40, v40, v204
	v_mul_f32_e32 v41, v41, v204
	v_mul_f32_e32 v42, v42, v204
	v_mul_f32_e32 v43, v43, v204
	v_cvt_pk_bf16_f32 v44, v44, v45
	v_cvt_pk_bf16_f32 v45, v46, v47
	v_cvt_pk_bf16_f32 v46, v40, v41
	v_cvt_pk_bf16_f32 v47, v42, v43
	global_store_dwordx4 v226, v[44:47], s[64:65]
	v_mul_f32_e32 v36, v36, v204
	v_mul_f32_e32 v37, v37, v204
	v_mul_f32_e32 v38, v38, v204
	v_mul_f32_e32 v39, v39, v204
	v_mul_f32_e32 v32, v32, v204
	v_mul_f32_e32 v33, v33, v204
	v_mul_f32_e32 v34, v34, v204
	v_mul_f32_e32 v35, v35, v204
	v_cvt_pk_bf16_f32 v36, v36, v37
	v_cvt_pk_bf16_f32 v37, v38, v39
	v_cvt_pk_bf16_f32 v38, v32, v33
	v_cvt_pk_bf16_f32 v39, v34, v35
	global_store_dwordx4 v225, v[36:39], s[74:75]
	s_waitcnt vmcnt(21)
	v_fmamk_f32 v205, v205, 0x3b000000, v207
	v_rsq_f32_e32 v205, v205
	s_add_u32 s64, s70, 0xf0000
	s_addc_u32 s65, s71, 0
	s_add_u32 s74, s72, 0xa0000
	s_addc_u32 s75, s73, 0
	v_mul_f32_e32 v28, v28, v205
	v_mul_f32_e32 v29, v29, v205
	v_mul_f32_e32 v30, v30, v205
	v_mul_f32_e32 v31, v31, v205
	v_mul_f32_e32 v24, v24, v205
	v_mul_f32_e32 v25, v25, v205
	v_mul_f32_e32 v26, v26, v205
	v_mul_f32_e32 v27, v27, v205
	v_cvt_pk_bf16_f32 v28, v28, v29
	v_cvt_pk_bf16_f32 v29, v30, v31
	v_cvt_pk_bf16_f32 v30, v24, v25
	v_cvt_pk_bf16_f32 v31, v26, v27
	global_store_dwordx4 v226, v[28:31], s[64:65]
	v_mul_f32_e32 v20, v20, v205
	v_mul_f32_e32 v21, v21, v205
	v_mul_f32_e32 v22, v22, v205
	v_mul_f32_e32 v23, v23, v205
	v_mul_f32_e32 v16, v16, v205
	v_mul_f32_e32 v17, v17, v205
	v_mul_f32_e32 v18, v18, v205
	v_mul_f32_e32 v19, v19, v205
	v_cvt_pk_bf16_f32 v20, v20, v21
	v_cvt_pk_bf16_f32 v21, v22, v23
	v_cvt_pk_bf16_f32 v22, v16, v17
	v_cvt_pk_bf16_f32 v23, v18, v19
	global_store_dwordx4 v225, v[20:23], s[74:75]
	s_waitcnt vmcnt(22)
	v_fmamk_f32 v224, v224, 0x3b000000, v207
	v_rsq_f32_e32 v224, v224
	s_add_u32 s64, s70, 0x108000
	s_addc_u32 s65, s71, 0
	s_add_u32 s74, s72, 0xb0000
	s_addc_u32 s75, s73, 0
	v_mul_f32_e32 v12, v12, v224
	v_mul_f32_e32 v13, v13, v224
	v_mul_f32_e32 v14, v14, v224
	v_mul_f32_e32 v15, v15, v224
	v_mul_f32_e32 v8, v8, v224
	v_mul_f32_e32 v9, v9, v224
	v_mul_f32_e32 v10, v10, v224
	v_mul_f32_e32 v11, v11, v224
	v_cvt_pk_bf16_f32 v12, v12, v13
	v_cvt_pk_bf16_f32 v13, v14, v15
	v_cvt_pk_bf16_f32 v14, v8, v9
	v_cvt_pk_bf16_f32 v15, v10, v11
	global_store_dwordx4 v226, v[12:15], s[64:65]
	v_mul_f32_e32 v4, v4, v224
	v_mul_f32_e32 v5, v5, v224
	v_mul_f32_e32 v6, v6, v224
	v_mul_f32_e32 v7, v7, v224
	v_mul_f32_e32 v0, v0, v224
	v_mul_f32_e32 v1, v1, v224
	v_mul_f32_e32 v2, v2, v224
	v_mul_f32_e32 v3, v3, v224
	v_cvt_pk_bf16_f32 v4, v4, v5
	v_cvt_pk_bf16_f32 v5, v6, v7
	v_cvt_pk_bf16_f32 v6, v0, v1
	v_cvt_pk_bf16_f32 v7, v2, v3
	global_store_dwordx4 v225, v[4:7], s[74:75]
	s_cmp_eq_u32 s30, 0
	s_cbranch_scc1 .Lmy_kv_tail_nolat
; __device__ __forceinline__ int get_tid() { int t = __builtin_amdgcn_workitem_id_x(); asm volatile("" : "+v"(t)); return t; }
; __device__ __forceinline__ u32x4 pack8(f32x4 v0, f32x4 v1) { u32x4 w; w.x = cvt_pk_bf16(v0[0], v0[1]); w.y = cvt_pk_bf16(v0[2], v0[3]); w.z = cvt_pk_bf16(v1[0], v1[1]); w.w = cvt_pk_bf16(v1[2], v1[3]); return w; }
;     __device__ __forceinline__ void operator()(EPI_ARGS) const {
;     ...
;         { const int tid = get_tid(), row = u.pm * BM + (tid >> 1), half = tid & 1; const int s = row % SB; const bool lat = s >= CTXL; const int t = s - CTXL;
;           const float* kr = MISC + (size_t)row * MISC_LD + 32 + half * 32; bf16_t* dst = KB + (size_t)row * KLD + u.pn * 192 + 128 + half * 32;
; #pragma unroll
;           for (int c = 0; c < 4; ++c) { f32x4 v0 = *(const f32x4*)(kr + c * 8), v1 = *(const f32x4*)(kr + c * 8 + 4);
;               if (lat) { const float* rp = ROPE + ((size_t)t * 32 + half * 16 + c * 4) * 2; const f32x4 r0 = *(const f32x4*)rp, r1 = *(const f32x4*)(rp + 4);
;                   f32x4 o0, o1;
;                   o0[0] = v0[0] * r0[0] - v0[1] * r0[1]; o0[1] = v0[0] * r0[1] + v0[1] * r0[0]; o0[2] = v0[2] * r0[2] - v0[3] * r0[3]; o0[3] = v0[2] * r0[3] + v0[3] * r0[2];
;                   o1[0] = v1[0] * r1[0] - v1[1] * r1[1]; o1[1] = v1[0] * r1[1] + v1[1] * r1[0]; o1[2] = v1[2] * r1[2] - v1[3] * r1[3]; o1[3] = v1[2] * r1[3] + v1[3] * r1[2];
;                   v0 = o0; v1 = o1; }
;               *(u32x4*)(dst + c * 8) = pack8(v0, v1); asm volatile("" ::: "memory"); } }
	s_waitcnt vmcnt(16)
	v_mul_f32_e32 v140, v149, v185
	v_mul_f32_e32 v141, v149, v184
	v_fma_f32 v149, v148, v185, v141
	v_fma_f32 v148, v148, v184, -v140
	v_mul_f32_e32 v140, v151, v187
	v_mul_f32_e32 v141, v151, v186
	v_fma_f32 v151, v150, v187, v141
	v_fma_f32 v150, v150, v186, -v140
	v_mul_f32_e32 v140, v153, v189
	v_mul_f32_e32 v141, v153, v188
	v_fma_f32 v153, v152, v189, v141
	v_fma_f32 v152, v152, v188, -v140
	v_mul_f32_e32 v140, v155, v191
	v_mul_f32_e32 v141, v155, v190
	v_fma_f32 v155, v154, v191, v141
	v_fma_f32 v154, v154, v190, -v140
	v_cvt_pk_bf16_f32 v148, v148, v149
	v_cvt_pk_bf16_f32 v149, v150, v151
	v_cvt_pk_bf16_f32 v150, v152, v153
	v_cvt_pk_bf16_f32 v151, v154, v155
	global_store_dwordx4 v227, v[148:151], s[70:71] offset:256
	v_mul_f32_e32 v140, v157, v193
	v_mul_f32_e32 v141, v157, v192
	v_fma_f32 v157, v156, v193, v141
	v_fma_f32 v156, v156, v192, -v140
	v_mul_f32_e32 v140, v159, v195
	v_mul_f32_e32 v141, v159, v194
	v_fma_f32 v159, v158, v195, v141
	v_fma_f32 v158, v158, v194, -v140
	v_mul_f32_e32 v140, v165, v197
	v_mul_f32_e32 v141, v165, v196
	v_fma_f32 v165, v164, v197, v141
	v_fma_f32 v164, v164, v196, -v140
	v_mul_f32_e32 v140, v167, v199
	v_mul_f32_e32 v141, v167, v198
	v_fma_f32 v167, v166, v199, v141
	v_fma_f32 v166, v166, v198, -v140
	v_cvt_pk_bf16_f32 v156, v156, v157
	v_cvt_pk_bf16_f32 v157, v158, v159
	v_cvt_pk_bf16_f32 v158, v164, v165
	v_cvt_pk_bf16_f32 v159, v166, v167
	global_store_dwordx4 v227, v[156:159], s[70:71] offset:272
	v_mul_f32_e32 v140, v169, v201
	v_mul_f32_e32 v141, v169, v200
	v_fma_f32 v169, v168, v201, v141
	v_fma_f32 v168, v168, v200, -v140
	v_mul_f32_e32 v140, v171, v203
	v_mul_f32_e32 v141, v171, v202
	v_fma_f32 v171, v170, v203, v141
	v_fma_f32 v170, v170, v202, -v140
	v_mul_f32_e32 v140, v173, v209
	v_mul_f32_e32 v141, v173, v208
	v_fma_f32 v173, v172, v209, v141
	v_fma_f32 v172, v172, v208, -v140
	v_mul_f32_e32 v140, v175, v211
	v_mul_f32_e32 v141, v175, v210
	v_fma_f32 v175, v174, v211, v141
	v_fma_f32 v174, v174, v210, -v140
	v_cvt_pk_bf16_f32 v168, v168, v169
	v_cvt_pk_bf16_f32 v169, v170, v171
	v_cvt_pk_bf16_f32 v170, v172, v173
	v_cvt_pk_bf16_f32 v171, v174, v175
	global_store_dwordx4 v227, v[168:171], s[70:71] offset:288
	v_mul_f32_e32 v140, v177, v217
	v_mul_f32_e32 v141, v177, v216
	v_fma_f32 v177, v176, v217, v141
	v_fma_f32 v176, v176, v216, -v140
	v_mul_f32_e32 v140, v179, v219
	v_mul_f32_e32 v141, v179, v218
	v_fma_f32 v179, v178, v219, v141
	v_fma_f32 v178, v178, v218, -v140
	v_mul_f32_e32 v140, v181, v221
	v_mul_f32_e32 v141, v181, v220
	v_fma_f32 v181, v180, v221, v141
	v_fma_f32 v180, v180, v220, -v140
	v_mul_f32_e32 v140, v183, v223
	v_mul_f32_e32 v141, v183, v222
	v_fma_f32 v183, v182, v223, v141
	v_fma_f32 v182, v182, v222, -v140
	v_cvt_pk_bf16_f32 v176, v176, v177
	v_cvt_pk_bf16_f32 v177, v178, v179
	v_cvt_pk_bf16_f32 v178, v180, v181
	v_cvt_pk_bf16_f32 v179, v182, v183
	global_store_dwordx4 v227, v[176:179], s[70:71] offset:304
	s_branch .Lmy_kv_done
.Lmy_kv_tail_nolat:
	s_waitcnt vmcnt(16)
	v_cvt_pk_bf16_f32 v148, v148, v149
	v_cvt_pk_bf16_f32 v149, v150, v151
	v_cvt_pk_bf16_f32 v150, v152, v153
	v_cvt_pk_bf16_f32 v151, v154, v155
	global_store_dwordx4 v227, v[148:151], s[70:71] offset:256
	v_cvt_pk_bf16_f32 v156, v156, v157
	v_cvt_pk_bf16_f32 v157, v158, v159
	v_cvt_pk_bf16_f32 v158, v164, v165
	v_cvt_pk_bf16_f32 v159, v166, v167
	global_store_dwordx4 v227, v[156:159], s[70:71] offset:272
	v_cvt_pk_bf16_f32 v168, v168, v169
	v_cvt_pk_bf16_f32 v169, v170, v171
	v_cvt_pk_bf16_f32 v170, v172, v173
	v_cvt_pk_bf16_f32 v171, v174, v175
	global_store_dwordx4 v227, v[168:171], s[70:71] offset:288
	v_cvt_pk_bf16_f32 v176, v176, v177
	v_cvt_pk_bf16_f32 v177, v178, v179
	v_cvt_pk_bf16_f32 v178, v180, v181
	v_cvt_pk_bf16_f32 v179, v182, v183
	global_store_dwordx4 v227, v[176:179], s[70:71] offset:304
.Lmy_kv_done:
	s_and_b64 vcc, exec, s[2:3]
	s_mov_b64 s[2:3], -1
	s_cbranch_vccnz .LBB0_1219
	s_andn2_b64 vcc, exec, s[12:13]
	s_cbranch_vccnz .LBB0_1218
	s_barrier
	s_branch .LBB0_1218

; __device__ __forceinline__ u32x4 pack8(f32x4 v0, f32x4 v1) { u32x4 w; w.x = cvt_pk_bf16(v0[0], v0[1]); w.y = cvt_pk_bf16(v0[2], v0[3]); w.z = cvt_pk_bf16(v1[0], v1[1]); w.w = cvt_pk_bf16(v1[2], v1[3]); return w; }
; __device__ __forceinline__ float sigmoidf_(float x) { return 1.f / (1.f + __expf(-x)); }
;     __device__ __forceinline__ void operator()(EPI_ARGS) const {
;         const int row0 = u.pm * BM + wr * 64 + fr; const int col0 = u.pn * 128 + wc * 32 + 8 * fq;
; #pragma unroll
;         for (int ai = 0; ai < 2; ++ai)
; #pragma unroll
;             for (int m = 0; m < 4; ++m) { f32x4 o[2];
; #pragma unroll
;                 for (int n = 0; n < 2; ++n)
; #pragma unroll
;                     for (int j = 0; j < 4; ++j) { const float gt = acc[ai][0][m][n][j]; o[n][j] = gt * sigmoidf_(gt) * acc[ai][1][m][n][j]; }
;                 *(u32x4*)(U + (size_t)(row0 + ai * HALF + m * 16) * DFF + col0) = pack8(o[0], o[1]); }
;     }
.LBB0_2221:
	v_lshl_add_u32 v138, s68, 8, v141
	v_lshl_or_b32 v139, s70, 7, v143
	v_mul_u32_u24_e32 v151, 0x2c00, v138
	v_lshl_add_u32 v151, v139, 1, v151
	s_mov_b64 s[68:69], -1
	v_mul_f32_e32 v138, 0xbfb8aa3b, v124
	v_mul_f32_e32 v139, 0xbfb8aa3b, v125
	v_mul_f32_e32 v145, 0xbfb8aa3b, v126
	v_mul_f32_e32 v146, 0xbfb8aa3b, v127
	v_mul_f32_e32 v147, 0xbfb8aa3b, v116
	v_mul_f32_e32 v148, 0xbfb8aa3b, v117
	v_mul_f32_e32 v149, 0xbfb8aa3b, v118
	v_mul_f32_e32 v150, 0xbfb8aa3b, v119
	v_exp_f32_e32 v138, v138
	v_exp_f32_e32 v139, v139
	v_exp_f32_e32 v145, v145
	v_exp_f32_e32 v146, v146
	v_exp_f32_e32 v147, v147
	v_exp_f32_e32 v148, v148
	v_exp_f32_e32 v149, v149
	v_exp_f32_e32 v150, v150
	v_add_f32_e32 v138, 1.0, v138
	v_add_f32_e32 v139, 1.0, v139
	v_add_f32_e32 v145, 1.0, v145
	v_add_f32_e32 v146, 1.0, v146
	v_add_f32_e32 v147, 1.0, v147
	v_add_f32_e32 v148, 1.0, v148
	v_add_f32_e32 v149, 1.0, v149
	v_add_f32_e32 v150, 1.0, v150
	v_rcp_f32_e32 v138, v138
	v_rcp_f32_e32 v139, v139
	v_rcp_f32_e32 v145, v145
	v_rcp_f32_e32 v146, v146
	v_rcp_f32_e32 v147, v147
	v_rcp_f32_e32 v148, v148
	v_rcp_f32_e32 v149, v149
	v_rcp_f32_e32 v150, v150
	v_mul_f32_e32 v124, v124, v138
	v_mul_f32_e32 v125, v125, v139
	v_mul_f32_e32 v126, v126, v145
	v_mul_f32_e32 v127, v127, v146
	v_mul_f32_e32 v116, v116, v147
	v_mul_f32_e32 v117, v117, v148
	v_mul_f32_e32 v118, v118, v149
	v_mul_f32_e32 v119, v119, v150
	v_mul_f32_e32 v124, v124, v120
	v_mul_f32_e32 v125, v125, v121
	v_mul_f32_e32 v126, v126, v122
	v_mul_f32_e32 v127, v127, v123
	v_mul_f32_e32 v116, v116, v112
	v_mul_f32_e32 v117, v117, v113
	v_mul_f32_e32 v118, v118, v114
	v_mul_f32_e32 v119, v119, v115
	v_cvt_pk_bf16_f32 v124, v124, v125
	v_cvt_pk_bf16_f32 v125, v126, v127
	v_cvt_pk_bf16_f32 v126, v116, v117
	v_cvt_pk_bf16_f32 v127, v118, v119
	global_store_dwordx4 v151, v[124:127], s[16:17]
	v_mul_f32_e32 v138, 0xbfb8aa3b, v108
	v_mul_f32_e32 v139, 0xbfb8aa3b, v109
	v_mul_f32_e32 v145, 0xbfb8aa3b, v110
	v_mul_f32_e32 v146, 0xbfb8aa3b, v111
	v_mul_f32_e32 v147, 0xbfb8aa3b, v100
	v_mul_f32_e32 v148, 0xbfb8aa3b, v101
	v_mul_f32_e32 v149, 0xbfb8aa3b, v102
	v_mul_f32_e32 v150, 0xbfb8aa3b, v103
	v_exp_f32_e32 v138, v138
	v_exp_f32_e32 v139, v139
	v_exp_f32_e32 v145, v145
	v_exp_f32_e32 v146, v146
	v_exp_f32_e32 v147, v147
	v_exp_f32_e32 v148, v148
	v_exp_f32_e32 v149, v149
	v_exp_f32_e32 v150, v150
	v_add_f32_e32 v138, 1.0, v138
	v_add_f32_e32 v139, 1.0, v139
	v_add_f32_e32 v145, 1.0, v145
	v_add_f32_e32 v146, 1.0, v146
	v_add_f32_e32 v147, 1.0, v147
	v_add_f32_e32 v148, 1.0, v148
	v_add_f32_e32 v149, 1.0, v149
	v_add_f32_e32 v150, 1.0, v150
	v_rcp_f32_e32 v138, v138
	v_rcp_f32_e32 v139, v139
	v_rcp_f32_e32 v145, v145
	v_rcp_f32_e32 v146, v146
	v_rcp_f32_e32 v147, v147
	v_rcp_f32_e32 v148, v148
	v_rcp_f32_e32 v149, v149
	v_rcp_f32_e32 v150, v150
	v_mul_f32_e32 v108, v108, v138
	v_mul_f32_e32 v109, v109, v139
	v_mul_f32_e32 v110, v110, v145
	v_mul_f32_e32 v111, v111, v146
	v_mul_f32_e32 v100, v100, v147
	v_mul_f32_e32 v101, v101, v148
	v_mul_f32_e32 v102, v102, v149
	v_mul_f32_e32 v103, v103, v150
	v_mul_f32_e32 v108, v108, v104
	v_mul_f32_e32 v109, v109, v105
	v_mul_f32_e32 v110, v110, v106
	v_mul_f32_e32 v111, v111, v107
	v_mul_f32_e32 v100, v100, v96
	v_mul_f32_e32 v101, v101, v97
	v_mul_f32_e32 v102, v102, v98
	v_mul_f32_e32 v103, v103, v99
	v_cvt_pk_bf16_f32 v108, v108, v109
	v_cvt_pk_bf16_f32 v109, v110, v111
	v_cvt_pk_bf16_f32 v110, v100, v101
	v_cvt_pk_bf16_f32 v111, v102, v103
	s_add_u32 s36, s16, 0x2c000
	s_addc_u32 s37, s17, 0
	global_store_dwordx4 v151, v[108:111], s[36:37]
	v_mul_f32_e32 v138, 0xbfb8aa3b, v92
	v_mul_f32_e32 v139, 0xbfb8aa3b, v93
	v_mul_f32_e32 v145, 0xbfb8aa3b, v94
	v_mul_f32_e32 v146, 0xbfb8aa3b, v95
	v_mul_f32_e32 v147, 0xbfb8aa3b, v84
	v_mul_f32_e32 v148, 0xbfb8aa3b, v85
	v_mul_f32_e32 v149, 0xbfb8aa3b, v86
	v_mul_f32_e32 v150, 0xbfb8aa3b, v87
	v_exp_f32_e32 v138, v138
	v_exp_f32_e32 v139, v139
	v_exp_f32_e32 v145, v145
	v_exp_f32_e32 v146, v146
	v_exp_f32_e32 v147, v147
	v_exp_f32_e32 v148, v148
	v_exp_f32_e32 v149, v149
	v_exp_f32_e32 v150, v150
	v_add_f32_e32 v138, 1.0, v138
	v_add_f32_e32 v139, 1.0, v139
	v_add_f32_e32 v145, 1.0, v145
	v_add_f32_e32 v146, 1.0, v146
	v_add_f32_e32 v147, 1.0, v147
	v_add_f32_e32 v148, 1.0, v148
	v_add_f32_e32 v149, 1.0, v149
	v_add_f32_e32 v150, 1.0, v150
	v_rcp_f32_e32 v138, v138
	v_rcp_f32_e32 v139, v139
	v_rcp_f32_e32 v145, v145
	v_rcp_f32_e32 v146, v146
	v_rcp_f32_e32 v147, v147
	v_rcp_f32_e32 v148, v148
	v_rcp_f32_e32 v149, v149
	v_rcp_f32_e32 v150, v150
	v_mul_f32_e32 v92, v92, v138
	v_mul_f32_e32 v93, v93, v139
	v_mul_f32_e32 v94, v94, v145
	v_mul_f32_e32 v95, v95, v146
	v_mul_f32_e32 v84, v84, v147
	v_mul_f32_e32 v85, v85, v148
	v_mul_f32_e32 v86, v86, v149
	v_mul_f32_e32 v87, v87, v150
	v_mul_f32_e32 v92, v92, v88
	v_mul_f32_e32 v93, v93, v89
	v_mul_f32_e32 v94, v94, v90
	v_mul_f32_e32 v95, v95, v91
	v_mul_f32_e32 v84, v84, v80
	v_mul_f32_e32 v85, v85, v81
	v_mul_f32_e32 v86, v86, v82
	v_mul_f32_e32 v87, v87, v83
	v_cvt_pk_bf16_f32 v92, v92, v93
	v_cvt_pk_bf16_f32 v93, v94, v95
	v_cvt_pk_bf16_f32 v94, v84, v85
	v_cvt_pk_bf16_f32 v95, v86, v87
	s_add_u32 s36, s16, 0x58000
	s_addc_u32 s37, s17, 0
	global_store_dwordx4 v151, v[92:95], s[36:37]
	v_mul_f32_e32 v138, 0xbfb8aa3b, v76
	v_mul_f32_e32 v139, 0xbfb8aa3b, v77
	v_mul_f32_e32 v145, 0xbfb8aa3b, v78
	v_mul_f32_e32 v146, 0xbfb8aa3b, v79
	v_mul_f32_e32 v147, 0xbfb8aa3b, v68
	v_mul_f32_e32 v148, 0xbfb8aa3b, v69
	v_mul_f32_e32 v149, 0xbfb8aa3b, v70
	v_mul_f32_e32 v150, 0xbfb8aa3b, v71
	v_exp_f32_e32 v138, v138
	v_exp_f32_e32 v139, v139
	v_exp_f32_e32 v145, v145
	v_exp_f32_e32 v146, v146
; __device__ __forceinline__ u32x4 pack8(f32x4 v0, f32x4 v1) { u32x4 w; w.x = cvt_pk_bf16(v0[0], v0[1]); w.y = cvt_pk_bf16(v0[2], v0[3]); w.z = cvt_pk_bf16(v1[0], v1[1]); w.w = cvt_pk_bf16(v1[2], v1[3]); return w; }
; __device__ __forceinline__ float sigmoidf_(float x) { return 1.f / (1.f + __expf(-x)); }
;     __device__ __forceinline__ void operator()(EPI_ARGS) const {
;         const int row0 = u.pm * BM + wr * 64 + fr; const int col0 = u.pn * 128 + wc * 32 + 8 * fq;
; #pragma unroll
;         for (int ai = 0; ai < 2; ++ai)
; #pragma unroll
;             for (int m = 0; m < 4; ++m) { f32x4 o[2];
; #pragma unroll
;                 for (int n = 0; n < 2; ++n)
; #pragma unroll
;                     for (int j = 0; j < 4; ++j) { const float gt = acc[ai][0][m][n][j]; o[n][j] = gt * sigmoidf_(gt) * acc[ai][1][m][n][j]; }
;                 *(u32x4*)(U + (size_t)(row0 + ai * HALF + m * 16) * DFF + col0) = pack8(o[0], o[1]); }
;     }
	v_exp_f32_e32 v147, v147
	v_exp_f32_e32 v148, v148
	v_exp_f32_e32 v149, v149
	v_exp_f32_e32 v150, v150
	v_add_f32_e32 v138, 1.0, v138
	v_add_f32_e32 v139, 1.0, v139
	v_add_f32_e32 v145, 1.0, v145
	v_add_f32_e32 v146, 1.0, v146
	v_add_f32_e32 v147, 1.0, v147
	v_add_f32_e32 v148, 1.0, v148
	v_add_f32_e32 v149, 1.0, v149
	v_add_f32_e32 v150, 1.0, v150
	v_rcp_f32_e32 v138, v138
	v_rcp_f32_e32 v139, v139
	v_rcp_f32_e32 v145, v145
	v_rcp_f32_e32 v146, v146
	v_rcp_f32_e32 v147, v147
	v_rcp_f32_e32 v148, v148
	v_rcp_f32_e32 v149, v149
	v_rcp_f32_e32 v150, v150
	v_mul_f32_e32 v76, v76, v138
	v_mul_f32_e32 v77, v77, v139
	v_mul_f32_e32 v78, v78, v145
	v_mul_f32_e32 v79, v79, v146
	v_mul_f32_e32 v68, v68, v147
	v_mul_f32_e32 v69, v69, v148
	v_mul_f32_e32 v70, v70, v149
	v_mul_f32_e32 v71, v71, v150
	v_mul_f32_e32 v76, v76, v72
	v_mul_f32_e32 v77, v77, v73
	v_mul_f32_e32 v78, v78, v74
	v_mul_f32_e32 v79, v79, v75
	v_mul_f32_e32 v68, v68, v64
	v_mul_f32_e32 v69, v69, v65
	v_mul_f32_e32 v70, v70, v66
	v_mul_f32_e32 v71, v71, v67
	v_cvt_pk_bf16_f32 v76, v76, v77
	v_cvt_pk_bf16_f32 v77, v78, v79
	v_cvt_pk_bf16_f32 v78, v68, v69
	v_cvt_pk_bf16_f32 v79, v70, v71
	s_add_u32 s36, s16, 0x84000
	s_addc_u32 s37, s17, 0
	global_store_dwordx4 v151, v[76:79], s[36:37]
	v_mul_f32_e32 v138, 0xbfb8aa3b, v60
	v_mul_f32_e32 v139, 0xbfb8aa3b, v61
	v_mul_f32_e32 v145, 0xbfb8aa3b, v62
	v_mul_f32_e32 v146, 0xbfb8aa3b, v63
	v_mul_f32_e32 v147, 0xbfb8aa3b, v52
	v_mul_f32_e32 v148, 0xbfb8aa3b, v53
	v_mul_f32_e32 v149, 0xbfb8aa3b, v54
	v_mul_f32_e32 v150, 0xbfb8aa3b, v55
	v_exp_f32_e32 v138, v138
	v_exp_f32_e32 v139, v139
	v_exp_f32_e32 v145, v145
	v_exp_f32_e32 v146, v146
	v_exp_f32_e32 v147, v147
	v_exp_f32_e32 v148, v148
	v_exp_f32_e32 v149, v149
	v_exp_f32_e32 v150, v150
	v_add_f32_e32 v138, 1.0, v138
	v_add_f32_e32 v139, 1.0, v139
	v_add_f32_e32 v145, 1.0, v145
	v_add_f32_e32 v146, 1.0, v146
	v_add_f32_e32 v147, 1.0, v147
	v_add_f32_e32 v148, 1.0, v148
	v_add_f32_e32 v149, 1.0, v149
	v_add_f32_e32 v150, 1.0, v150
	v_rcp_f32_e32 v138, v138
	v_rcp_f32_e32 v139, v139
	v_rcp_f32_e32 v145, v145
	v_rcp_f32_e32 v146, v146
	v_rcp_f32_e32 v147, v147
	v_rcp_f32_e32 v148, v148
	v_rcp_f32_e32 v149, v149
	v_rcp_f32_e32 v150, v150
	v_mul_f32_e32 v60, v60, v138
	v_mul_f32_e32 v61, v61, v139
	v_mul_f32_e32 v62, v62, v145
	v_mul_f32_e32 v63, v63, v146
	v_mul_f32_e32 v52, v52, v147
	v_mul_f32_e32 v53, v53, v148
	v_mul_f32_e32 v54, v54, v149
	v_mul_f32_e32 v55, v55, v150
	v_mul_f32_e32 v60, v60, v56
	v_mul_f32_e32 v61, v61, v57
	v_mul_f32_e32 v62, v62, v58
	v_mul_f32_e32 v63, v63, v59
	v_mul_f32_e32 v52, v52, v48
	v_mul_f32_e32 v53, v53, v49
	v_mul_f32_e32 v54, v54, v50
	v_mul_f32_e32 v55, v55, v51
	v_cvt_pk_bf16_f32 v60, v60, v61
	v_cvt_pk_bf16_f32 v61, v62, v63
	v_cvt_pk_bf16_f32 v62, v52, v53
	v_cvt_pk_bf16_f32 v63, v54, v55
	s_add_u32 s36, s16, 0x160000
	s_addc_u32 s37, s17, 0
	global_store_dwordx4 v151, v[60:63], s[36:37]
	v_mul_f32_e32 v138, 0xbfb8aa3b, v44
	v_mul_f32_e32 v139, 0xbfb8aa3b, v45
	v_mul_f32_e32 v145, 0xbfb8aa3b, v46
	v_mul_f32_e32 v146, 0xbfb8aa3b, v47
	v_mul_f32_e32 v147, 0xbfb8aa3b, v36
	v_mul_f32_e32 v148, 0xbfb8aa3b, v37
	v_mul_f32_e32 v149, 0xbfb8aa3b, v38
	v_mul_f32_e32 v150, 0xbfb8aa3b, v39
	v_exp_f32_e32 v138, v138
	v_exp_f32_e32 v139, v139
	v_exp_f32_e32 v145, v145
	v_exp_f32_e32 v146, v146
	v_exp_f32_e32 v147, v147
	v_exp_f32_e32 v148, v148
	v_exp_f32_e32 v149, v149
	v_exp_f32_e32 v150, v150
	v_add_f32_e32 v138, 1.0, v138
	v_add_f32_e32 v139, 1.0, v139
	v_add_f32_e32 v145, 1.0, v145
	v_add_f32_e32 v146, 1.0, v146
	v_add_f32_e32 v147, 1.0, v147
	v_add_f32_e32 v148, 1.0, v148
	v_add_f32_e32 v149, 1.0, v149
	v_add_f32_e32 v150, 1.0, v150
	v_rcp_f32_e32 v138, v138
	v_rcp_f32_e32 v139, v139
	v_rcp_f32_e32 v145, v145
	v_rcp_f32_e32 v146, v146
	v_rcp_f32_e32 v147, v147
	v_rcp_f32_e32 v148, v148
	v_rcp_f32_e32 v149, v149
	v_rcp_f32_e32 v150, v150
	v_mul_f32_e32 v44, v44, v138
	v_mul_f32_e32 v45, v45, v139
	v_mul_f32_e32 v46, v46, v145
	v_mul_f32_e32 v47, v47, v146
; __device__ __forceinline__ float sigmoidf_(float x) { return 1.f / (1.f + __expf(-x)); }
; __device__ __forceinline__ u32x4 pack8(f32x4 v0, f32x4 v1) { u32x4 w; w.x = cvt_pk_bf16(v0[0], v0[1]); w.y = cvt_pk_bf16(v0[2], v0[3]); w.z = cvt_pk_bf16(v1[0], v1[1]); w.w = cvt_pk_bf16(v1[2], v1[3]); return w; }
;     __device__ __forceinline__ void operator()(EPI_ARGS) const {
;         const int row0 = u.pm * BM + wr * 64 + fr; const int col0 = u.pn * 128 + wc * 32 + 8 * fq;
; #pragma unroll
;         for (int ai = 0; ai < 2; ++ai)
; #pragma unroll
;             for (int m = 0; m < 4; ++m) { f32x4 o[2];
; #pragma unroll
;                 for (int n = 0; n < 2; ++n)
; #pragma unroll
;                     for (int j = 0; j < 4; ++j) { const float gt = acc[ai][0][m][n][j]; o[n][j] = gt * sigmoidf_(gt) * acc[ai][1][m][n][j]; }
;                 *(u32x4*)(U + (size_t)(row0 + ai * HALF + m * 16) * DFF + col0) = pack8(o[0], o[1]); }
;     }
	v_mul_f32_e32 v36, v36, v147
	v_mul_f32_e32 v37, v37, v148
	v_mul_f32_e32 v38, v38, v149
	v_mul_f32_e32 v39, v39, v150
	v_mul_f32_e32 v44, v44, v40
	v_mul_f32_e32 v45, v45, v41
	v_mul_f32_e32 v46, v46, v42
	v_mul_f32_e32 v47, v47, v43
	v_mul_f32_e32 v36, v36, v32
	v_mul_f32_e32 v37, v37, v33
	v_mul_f32_e32 v38, v38, v34
	v_mul_f32_e32 v39, v39, v35
	v_cvt_pk_bf16_f32 v44, v44, v45
	v_cvt_pk_bf16_f32 v45, v46, v47
	v_cvt_pk_bf16_f32 v46, v36, v37
	v_cvt_pk_bf16_f32 v47, v38, v39
	s_add_u32 s36, s16, 0x18c000
	s_addc_u32 s37, s17, 0
	global_store_dwordx4 v151, v[44:47], s[36:37]
	v_mul_f32_e32 v138, 0xbfb8aa3b, v28
	v_mul_f32_e32 v139, 0xbfb8aa3b, v29
	v_mul_f32_e32 v145, 0xbfb8aa3b, v30
	v_mul_f32_e32 v146, 0xbfb8aa3b, v31
	v_mul_f32_e32 v147, 0xbfb8aa3b, v20
	v_mul_f32_e32 v148, 0xbfb8aa3b, v21
	v_mul_f32_e32 v149, 0xbfb8aa3b, v22
	v_mul_f32_e32 v150, 0xbfb8aa3b, v23
	v_exp_f32_e32 v138, v138
	v_exp_f32_e32 v139, v139
	v_exp_f32_e32 v145, v145
	v_exp_f32_e32 v146, v146
	v_exp_f32_e32 v147, v147
	v_exp_f32_e32 v148, v148
	v_exp_f32_e32 v149, v149
	v_exp_f32_e32 v150, v150
	v_add_f32_e32 v138, 1.0, v138
	v_add_f32_e32 v139, 1.0, v139
	v_add_f32_e32 v145, 1.0, v145
	v_add_f32_e32 v146, 1.0, v146
	v_add_f32_e32 v147, 1.0, v147
	v_add_f32_e32 v148, 1.0, v148
	v_add_f32_e32 v149, 1.0, v149
	v_add_f32_e32 v150, 1.0, v150
	v_rcp_f32_e32 v138, v138
	v_rcp_f32_e32 v139, v139
	v_rcp_f32_e32 v145, v145
	v_rcp_f32_e32 v146, v146
	v_rcp_f32_e32 v147, v147
	v_rcp_f32_e32 v148, v148
	v_rcp_f32_e32 v149, v149
	v_rcp_f32_e32 v150, v150
	v_mul_f32_e32 v28, v28, v138
	v_mul_f32_e32 v29, v29, v139
	v_mul_f32_e32 v30, v30, v145
	v_mul_f32_e32 v31, v31, v146
	v_mul_f32_e32 v20, v20, v147
	v_mul_f32_e32 v21, v21, v148
	v_mul_f32_e32 v22, v22, v149
	v_mul_f32_e32 v23, v23, v150
	v_mul_f32_e32 v28, v28, v24
	v_mul_f32_e32 v29, v29, v25
	v_mul_f32_e32 v30, v30, v26
	v_mul_f32_e32 v31, v31, v27
	v_mul_f32_e32 v20, v20, v16
	v_mul_f32_e32 v21, v21, v17
	v_mul_f32_e32 v22, v22, v18
	v_mul_f32_e32 v23, v23, v19
	v_cvt_pk_bf16_f32 v28, v28, v29
	v_cvt_pk_bf16_f32 v29, v30, v31
	v_cvt_pk_bf16_f32 v30, v20, v21
	v_cvt_pk_bf16_f32 v31, v22, v23
	s_add_u32 s36, s16, 0x1b8000
	s_addc_u32 s37, s17, 0
	global_store_dwordx4 v151, v[28:31], s[36:37]
	v_mul_f32_e32 v138, 0xbfb8aa3b, v12
	v_mul_f32_e32 v139, 0xbfb8aa3b, v13
	v_mul_f32_e32 v145, 0xbfb8aa3b, v14
	v_mul_f32_e32 v146, 0xbfb8aa3b, v15
	v_mul_f32_e32 v147, 0xbfb8aa3b, v4
	v_mul_f32_e32 v148, 0xbfb8aa3b, v5
	v_mul_f32_e32 v149, 0xbfb8aa3b, v6
	v_mul_f32_e32 v150, 0xbfb8aa3b, v7
	v_exp_f32_e32 v138, v138
	v_exp_f32_e32 v139, v139
	v_exp_f32_e32 v145, v145
	v_exp_f32_e32 v146, v146
	v_exp_f32_e32 v147, v147
	v_exp_f32_e32 v148, v148
	v_exp_f32_e32 v149, v149
	v_exp_f32_e32 v150, v150
	v_add_f32_e32 v138, 1.0, v138
	v_add_f32_e32 v139, 1.0, v139
	v_add_f32_e32 v145, 1.0, v145
	v_add_f32_e32 v146, 1.0, v146
	v_add_f32_e32 v147, 1.0, v147
	v_add_f32_e32 v148, 1.0, v148
	v_add_f32_e32 v149, 1.0, v149
	v_add_f32_e32 v150, 1.0, v150
	v_rcp_f32_e32 v138, v138
	v_rcp_f32_e32 v139, v139
	v_rcp_f32_e32 v145, v145
	v_rcp_f32_e32 v146, v146
	v_rcp_f32_e32 v147, v147
	v_rcp_f32_e32 v148, v148
	v_rcp_f32_e32 v149, v149
	v_rcp_f32_e32 v150, v150
	v_mul_f32_e32 v12, v12, v138
	v_mul_f32_e32 v13, v13, v139
	v_mul_f32_e32 v14, v14, v145
	v_mul_f32_e32 v15, v15, v146
	v_mul_f32_e32 v4, v4, v147
	v_mul_f32_e32 v5, v5, v148
	v_mul_f32_e32 v6, v6, v149
	v_mul_f32_e32 v7, v7, v150
	v_mul_f32_e32 v12, v12, v8
	v_mul_f32_e32 v13, v13, v9
	v_mul_f32_e32 v14, v14, v10
	v_mul_f32_e32 v15, v15, v11
	v_mul_f32_e32 v4, v4, v0
	v_mul_f32_e32 v5, v5, v1
	v_mul_f32_e32 v6, v6, v2
	v_mul_f32_e32 v7, v7, v3
	v_cvt_pk_bf16_f32 v12, v12, v13
	v_cvt_pk_bf16_f32 v13, v14, v15
	v_cvt_pk_bf16_f32 v14, v4, v5
	v_cvt_pk_bf16_f32 v15, v6, v7
	s_add_u32 s36, s16, 0x1e4000
	s_addc_u32 s37, s17, 0
	global_store_dwordx4 v151, v[12:15], s[36:37]
	s_andn2_b64 vcc, exec, s[4:5]
	s_cbranch_vccnz .LBB0_2213
	s_andn2_b64 vcc, exec, s[14:15]
	s_cbranch_vccnz .LBB0_2212
	s_barrier
	s_branch .LBB0_2212
